# RG-LRU gate GEMM: 18 per-wave weight fragments kept resident in unused VGPRs (loaded once per phase, flag-guarded), no per-item L2 reloads
# speedup vs baseline: 1.0165x; 1.0165x over previous
.LBB0_1068:
	s_and_b32 s30, s36, 7
	s_and_b32 s38, s37, 7
	s_mulk_i32 s30, 0x60
	s_cmp_eq_u32 s38, s24
	s_cbranch_scc1 .LBB0_1090
	s_mov_b32 s101, 0
	v_mov_b32_e32 v0, v224
	s_movk_i32 s3, 0x420
	s_barrier
	s_nop 0
	v_cmp_gt_i32_e32 vcc, s3, v0
	s_and_saveexec_b64 s[18:19], vcc
	s_cbranch_execz .LBB0_1089
	v_max_i32_e32 v1, 0x220, v0
	v_sub_u32_e32 v1, v1, v0
	v_add_u32_e32 v1, 0x1ff, v1
	s_movk_i32 s3, 0x1ff
	s_mul_i32 s31, s38, 0x60
	v_cmp_lt_u32_e32 vcc, s3, v1
	s_mov_b64 s[6:7], -1
	s_and_saveexec_b64 s[20:21], vcc
	s_cbranch_execz .LBB0_1074
	v_lshrrev_b32_e32 v1, 9, v1
	s_waitcnt vmcnt(1)
	v_add_u32_e32 v4, 1, v1
	s_add_i32 s24, s31, 0xfffffe80
	s_waitcnt vmcnt(0)
	v_and_b32_e32 v5, 0xfffffe, v4
	v_add_u32_e32 v1, 0x200, v0
	v_readlane_b32 s3, v255, 26
	s_mov_b32 s25, s31
	s_mov_b32 s34, s24
	v_lshl_add_u32 v6, v0, 2, s3
	s_mov_b64 s[22:23], 0
	v_mov_b32_e32 v7, v5
	v_mov_b64_e32 v[2:3], v[0:1]

.LBB0_1101:
	s_or_b64 exec, exec, s[20:21]
	v_bfe_u32 v77, v67, 6, 1
	v_lshl_or_b32 v0, v77, 4, s38
	v_and_b32_e32 v70, 15, v67
	v_bfe_u32 v66, v67, 4, 2
	v_mul_u32_u24_e32 v0, 0x60, v0
	v_lshlrev_b32_e32 v112, 4, v66
	v_lshrrev_b32_e32 v73, 8, v67
	v_or_b32_e32 v34, v0, v70
	v_lshl_add_u64 v[64:65], s[12:13], 0, v[112:113]
	v_mad_i32_i24 v0, v73, 48, v34
	v_mad_i64_i32 v[68:69], s[20:21], v0, s94, v[64:65]
	s_waitcnt lgkmcnt(0)
	s_barrier
	s_cmp_lg_u32 s101, 0
	s_cbranch_scc1 .Llruw0_0
	global_load_dwordx4 v[132:135], v[68:69], off
.Llruw0_0:
	s_waitcnt vmcnt(1)
	v_lshlrev_b32_e32 v4, 2, v67
	v_bfe_u32 v92, v67, 7, 1
	s_waitcnt vmcnt(0)
	v_lshlrev_b32_e32 v5, 6, v70
	v_and_b32_e32 v4, 32, v4
	v_mul_u32_u24_e32 v6, 0x1800, v92
	v_bitop3_b32 v4, v112, v4, v5 bitop3:0x36
	v_add3_u32 v93, 0, v4, v6
	ds_read_b128 v[20:23], v93
	ds_read_b128 v[8:11], v93 offset:3072
	v_mad_i32_i24 v72, v73, 48, 16
	v_add_u32_e32 v24, v34, v72
	v_mad_i64_i32 v[32:33], s[20:21], v24, s94, v[64:65]
	s_cmp_lg_u32 s101, 0
	s_cbranch_scc1 .Llruw0_1
	global_load_dwordx4 v[136:139], v[68:69], off offset:64
.Llruw0_1:
	v_mad_i32_i24 v71, v73, 48, 32
	v_add_u32_e32 v35, v34, v71
	v_mad_i64_i32 v[74:75], s[20:21], v35, s94, v[64:65]
	v_add_u32_e32 v76, 0x300, v34
	v_mad_i32_i24 v34, v73, 48, v76
	v_mad_i64_i32 v[90:91], s[20:21], v34, s94, v[64:65]
	ds_read_b128 v[12:15], v93 offset:1024
	v_lshlrev_b32_e32 v66, 2, v66
	v_readlane_b32 s3, v255, 27
	s_waitcnt vmcnt(0) lgkmcnt(2)
	v_mfma_f32_16x16x32_bf16 v[4:7], v[20:23], v[132:135], 0
	s_cmp_lg_u32 s101, 0
	s_cbranch_scc1 .Llruw0_2
	global_load_dwordx4 v[140:143], v[74:75], off offset:64
.Llruw0_2:
	s_waitcnt lgkmcnt(1)
	v_mfma_f32_16x16x32_bf16 v[24:27], v[8:11], v[132:135], 0
	s_cmp_lg_u32 s101, 0
	s_cbranch_scc1 .Llruw0_3
	global_load_dwordx4 v[144:147], v[32:33], off
.Llruw0_3:
	s_waitcnt vmcnt(0)
	v_mfma_f32_16x16x32_bf16 v[28:31], v[20:23], v[144:147], 0
	v_mfma_f32_16x16x32_bf16 v[40:43], v[8:11], v[144:147], 0
	s_cmp_lg_u32 s101, 0
	s_cbranch_scc1 .Llruw0_4
	global_load_dwordx4 v[148:151], v[74:75], off
.Llruw0_4:
	s_waitcnt lgkmcnt(0)
	v_mfma_f32_16x16x32_bf16 v[86:89], v[12:15], v[136:139], v[4:7]
	s_waitcnt vmcnt(0)
	v_mfma_f32_16x16x32_bf16 v[52:55], v[20:23], v[148:151], 0
	v_mfma_f32_16x16x32_bf16 v[60:63], v[8:11], v[148:151], 0
	s_cmp_lg_u32 s101, 0
	s_cbranch_scc1 .Llruw0_5
	global_load_dwordx4 v[152:155], v[90:91], off
.Llruw0_5:
	s_waitcnt vmcnt(0)
	v_mfma_f32_16x16x32_bf16 v[78:81], v[20:23], v[152:155], 0
	v_mfma_f32_16x16x32_bf16 v[82:85], v[8:11], v[152:155], 0
	ds_read_b128 v[4:7], v93 offset:4096
	ds_read_b128 v[0:3], v93 offset:5120
	s_waitcnt lgkmcnt(1)
	v_mfma_f32_16x16x32_bf16 v[48:51], v[4:7], v[136:139], v[24:27]
	s_cmp_lg_u32 s101, 0
	s_cbranch_scc1 .Llruw0_6
	global_load_dwordx4 v[156:159], v[32:33], off offset:64
.Llruw0_6:
	s_nop 0
	s_cmp_lg_u32 s101, 0
	s_cbranch_scc1 .Llruw0_7
	global_load_dwordx4 v[160:163], v[32:33], off offset:128
.Llruw0_7:
	s_waitcnt vmcnt(0)
	v_mfma_f32_16x16x32_bf16 v[56:59], v[4:7], v[156:159], v[40:43]
	s_cmp_lg_u32 s101, 0
	s_cbranch_scc1 .Llruw0_8
	global_load_dwordx4 v[164:167], v[90:91], off offset:64
.Llruw0_8:
	s_nop 1
	s_cmp_lg_u32 s101, 0
	s_cbranch_scc1 .Llruw0_9
	global_load_dwordx4 v[168:171], v[90:91], off offset:128
.Llruw0_9:
	v_mfma_f32_16x16x32_bf16 v[36:39], v[12:15], v[156:159], v[28:31]
	v_mfma_f32_16x16x32_bf16 v[16:19], v[4:7], v[140:143], v[60:63]
	v_mfma_f32_16x16x32_bf16 v[28:31], v[12:15], v[140:143], v[52:55]
	s_waitcnt vmcnt(0)
	v_mfma_f32_16x16x32_bf16 v[60:63], v[12:15], v[164:167], v[78:81]
	s_nop 2
	s_cmp_lg_u32 s101, 0
	s_cbranch_scc1 .Llruw0_10
	global_load_dwordx4 v[172:175], v[68:69], off offset:128
.Llruw0_10:
	v_mfma_f32_16x16x32_bf16 v[44:47], v[4:7], v[164:167], v[82:85]
	ds_read_b128 v[24:27], v93 offset:2048
	s_nop 1
	s_cmp_lg_u32 s101, 0
	s_cbranch_scc1 .Llruw0_11
	global_load_dwordx4 v[176:179], v[74:75], off offset:128
.Llruw0_11:
	v_mul_i32_i24_e32 v68, 48, v73
	v_or_b32_e32 v90, v68, v70
	v_mul_u32_u24_e32 v69, 0x300, v77
	v_mul_u32_u24_e32 v74, 0x180, v77
	s_waitcnt lgkmcnt(0)
	v_mfma_f32_16x16x32_bf16 v[36:39], v[24:27], v[160:163], v[36:39]
	v_mfma_f32_16x16x32_bf16 v[32:35], v[0:3], v[160:163], v[56:59]
	s_nop 2
	v_add_u32_e32 v56, v76, v72
	v_or_b32_e32 v72, v72, v70
	s_waitcnt vmcnt(0)
	v_mfma_f32_16x16x32_bf16 v[52:55], v[24:27], v[172:175], v[86:89]
	s_nop 2
	v_lshl_or_b32 v86, v92, 5, v66
	v_lshlrev_b32_e32 v66, 2, v90
	v_add3_u32 v73, s3, v69, v66
	v_mfma_f32_16x16x32_bf16 v[48:51], v[0:3], v[172:175], v[48:51]
	v_add_u32_e32 v91, 0, v66
	v_add3_u32 v74, s3, v74, v66
	v_mad_u32_u24 v75, v86, s47, v91
	v_mfma_f32_16x16x32_bf16 v[78:81], v[24:27], v[168:171], v[60:63]
	v_mul_u32_u24_e32 v94, 0x180, v86
	v_mad_i64_i32 v[68:69], s[20:21], v56, s94, v[64:65]
	s_waitcnt vmcnt(0)
	v_mfma_f32_16x16x32_bf16 v[28:31], v[24:27], v[176:179], v[28:31]
	s_movk_i32 s3, 0x480
	v_mfma_f32_16x16x32_bf16 v[16:19], v[0:3], v[176:179], v[16:19]
	ds_read_b32 v92, v73 offset:1920
	ds_read_b32 v93, v73 offset:2304
	ds_read_b32 v66, v74 offset:3456
	ds_read_b32 v82, v75 offset:12288
	s_cmp_lg_u32 s101, 0
	s_cbranch_scc1 .Llruw0_12
	global_load_dwordx4 v[180:183], v[68:69], off
.Llruw0_12:
	s_waitcnt lgkmcnt(3)
	v_add_f32_e32 v52, v52, v92
	v_mul_f32_e32 v52, 0xbfb8aa3b, v52
	s_waitcnt lgkmcnt(2)
	v_add_f32_e32 v60, v78, v93
	v_add_f32_e32 v53, v53, v92
	v_exp_f32_e32 v52, v52
	v_mul_f32_e32 v60, 0xbfb8aa3b, v60
	v_mul_f32_e32 v53, 0xbfb8aa3b, v53
	v_exp_f32_e32 v60, v60
	v_exp_f32_e32 v61, v53
	v_add_f32_e32 v52, 1.0, v52
	v_rcp_f32_e32 v53, v52
	v_add_f32_e32 v52, 1.0, v60
	v_rcp_f32_e32 v63, v52
	v_add_f32_e32 v52, 1.0, v61
	v_rcp_f32_e32 v52, v52
	v_add_f32_e32 v61, v79, v93
	v_lshl_or_b32 v60, v77, 6, v86
	v_mul_f32_e32 v61, 0xbfb8aa3b, v61
	v_pk_mul_f32 v[52:53], v[52:53], s[86:87] op_sel_hi:[1,0]
	v_mad_u32_u24 v77, v60, s46, v90
	s_waitcnt lgkmcnt(1)
	v_pk_mul_f32 v[52:53], v[66:67], v[52:53] op_sel_hi:[0,1]
	v_mul_f32_e32 v62, 0x3fb8aa3b, v53
	v_exp_f32_e32 v62, v62
	v_pk_add_f32 v[78:79], v[52:53], v[52:53]
	v_mul_f32_e32 v52, 0x3fb8aa3b, v52
	v_fma_f32 v53, v79, s66, 0.5
	v_fma_f32 v53, v79, v53, 1.0
	v_mul_f32_e32 v53, v79, v53
	v_fma_f32 v83, v62, v62, -1.0
	v_cmp_lt_f32_e32 vcc, s79, v79
	v_exp_f32_e32 v52, v52
	v_exp_f32_e32 v61, v61
	v_cndmask_b32_e32 v53, v83, v53, vcc
	v_max_f32_e64 v53, -v53, 0
	v_sqrt_f32_e32 v53, v53
	v_lshl_add_u32 v77, v77, 3, 0
	v_cmp_lt_f32_e32 vcc, s79, v78
	v_add_f32_e32 v61, 1.0, v61
	v_mul_f32_e32 v53, v63, v53
	s_waitcnt lgkmcnt(0)
	v_mul_f32_e32 v63, v82, v53
	v_fma_f32 v53, v78, s66, 0.5
	v_fma_f32 v53, v78, v53, 1.0
	ds_write_b64 v77, v[62:63] offset:36864
	v_mul_f32_e32 v53, v78, v53
	v_fma_f32 v62, v52, v52, -1.0
	v_cndmask_b32_e32 v53, v62, v53, vcc
	v_or_b32_e32 v62, 0x180, v94
	v_max_f32_e64 v53, -v53, 0
	v_add_u32_e32 v62, v91, v62
	v_rcp_f32_e32 v61, v61
	v_sqrt_f32_e32 v53, v53
	ds_read_b32 v63, v62 offset:12288
	v_mfma_f32_16x16x32_bf16 v[40:43], v[0:3], v[168:171], v[44:47]
	v_or_b32_e32 v77, 2, v60
	v_add_f32_e32 v48, v48, v92
	v_mul_f32_e32 v48, 0xbfb8aa3b, v48
	v_add_f32_e32 v45, v54, v92
	v_mul_f32_e32 v45, 0xbfb8aa3b, v45
	v_add_f32_e32 v46, v80, v93
	v_mul_f32_e32 v44, v61, v53
	v_exp_f32_e32 v45, v45
	v_mul_f32_e32 v46, 0xbfb8aa3b, v46
	s_waitcnt lgkmcnt(0)
	v_mul_f32_e32 v53, v63, v44
	v_or_b32_e32 v63, 1, v60
	v_exp_f32_e32 v46, v46
	v_mad_u32_u24 v44, v63, s46, v90
	v_lshl_add_u32 v44, v44, 3, 0
	ds_write_b64 v44, v[52:53] offset:36864
	v_add_f32_e32 v44, 1.0, v45
	v_rcp_f32_e32 v45, v44
	v_add_f32_e32 v44, 1.0, v46
	v_rcp_f32_e32 v47, v44
	v_add_f32_e32 v44, v55, v92
	v_mul_f32_e32 v44, 0xbfb8aa3b, v44
	v_exp_f32_e32 v44, v44
	v_add_f32_e32 v46, v81, v93
	v_mul_f32_e32 v46, 0xbfb8aa3b, v46
	v_exp_f32_e32 v78, v46
	v_add_f32_e32 v44, 1.0, v44
	v_rcp_f32_e32 v44, v44
	v_add3_u32 v61, v94, s54, v91
	ds_read_b32 v54, v61 offset:12288
	v_mad_u32_u24 v55, v77, s46, v90
	v_pk_mul_f32 v[44:45], v[44:45], s[86:87] op_sel_hi:[1,0]
	v_add_f32_e32 v40, v40, v93
	v_pk_mul_f32 v[44:45], v[66:67], v[44:45] op_sel_hi:[0,1]
	v_mul_f32_e32 v46, 0x3fb8aa3b, v45
	v_exp_f32_e32 v46, v46
	v_pk_add_f32 v[52:53], v[44:45], v[44:45]
	v_mul_f32_e32 v44, 0x3fb8aa3b, v44
	v_fma_f32 v45, v53, s66, 0.5
	v_fma_f32 v45, v53, v45, 1.0
	v_mul_f32_e32 v45, v53, v45
	v_fma_f32 v79, v46, v46, -1.0
	v_cmp_lt_f32_e32 vcc, s79, v53
	v_lshl_add_u32 v53, v55, 3, 0
	v_add_f32_e32 v55, 1.0, v78
	v_cndmask_b32_e32 v45, v79, v45, vcc
	v_max_f32_e64 v45, -v45, 0
	v_sqrt_f32_e32 v45, v45
	v_cmp_lt_f32_e32 vcc, s79, v52
	v_add3_u32 v79, v94, s3, v91
	v_mul_f32_e32 v40, 0xbfb8aa3b, v40
	v_mul_f32_e32 v45, v47, v45
	s_waitcnt lgkmcnt(0)
	v_mul_f32_e32 v47, v54, v45
	v_exp_f32_e32 v54, v44
	v_fma_f32 v44, v52, s66, 0.5
	v_fma_f32 v44, v52, v44, 1.0
	v_mul_f32_e32 v44, v52, v44
	v_fma_f32 v45, v54, v54, -1.0
	v_cndmask_b32_e32 v44, v45, v44, vcc
	ds_write_b64 v53, v[46:47] offset:36864
	v_max_f32_e64 v44, -v44, 0
	v_rcp_f32_e32 v55, v55
	v_sqrt_f32_e32 v52, v44
	ds_read_b32 v53, v79 offset:12288
	v_exp_f32_e32 v48, v48
	v_exp_f32_e32 v40, v40
	v_mul_f32_e32 v52, v55, v52
	v_or_b32_e32 v80, 3, v60
	v_add_f32_e32 v48, 1.0, v48
	v_add_f32_e32 v40, 1.0, v40
	s_waitcnt lgkmcnt(0)
	v_mul_f32_e32 v55, v53, v52
	v_rcp_f32_e32 v53, v48
	v_rcp_f32_e32 v48, v40
	v_add_f32_e32 v40, v49, v92
	v_mul_f32_e32 v40, 0xbfb8aa3b, v40
	v_exp_f32_e32 v40, v40
	v_mad_u32_u24 v52, v80, s46, v90
	v_lshl_add_u32 v52, v52, 3, 0
	ds_write_b64 v52, v[54:55] offset:36864
	v_add_f32_e32 v40, 1.0, v40
	v_rcp_f32_e32 v52, v40
	v_add_f32_e32 v40, v41, v93
	v_mul_f32_e32 v40, 0xbfb8aa3b, v40
	v_exp_f32_e32 v87, v40
	v_pk_mul_f32 v[40:41], v[52:53], s[86:87] op_sel_hi:[1,0]
	s_movk_i32 s3, 0x1800
	v_pk_mul_f32 v[40:41], v[66:67], v[40:41] op_sel_hi:[0,1]
	v_mul_f32_e32 v52, 0x3fb8aa3b, v41
	v_exp_f32_e32 v52, v52
	v_pk_add_f32 v[54:55], v[40:41], v[40:41]
	v_add3_u32 v78, v94, s3, v91
	v_fma_f32 v41, v55, s66, 0.5
	v_fma_f32 v41, v55, v41, 1.0
	v_mul_f32_e32 v41, v55, v41
	v_fma_f32 v53, v52, v52, -1.0
	v_cmp_lt_f32_e32 vcc, s79, v55
	ds_read_b32 v81, v78 offset:12288
	s_cmp_lg_u32 s101, 0
	s_cbranch_scc1 .Llruw0_13
	global_load_dwordx4 v[194:197], v[68:69], off offset:64
.Llruw0_13:
	v_cndmask_b32_e32 v41, v53, v41, vcc
	v_max_f32_e64 v41, -v41, 0
	v_sqrt_f32_e32 v41, v41
	v_or_b32_e32 v49, 16, v60
	v_add_f32_e32 v53, 1.0, v87
	v_mad_u32_u24 v86, v49, s46, v90
	v_mul_f32_e32 v41, v48, v41
	v_rcp_f32_e32 v95, v53
	s_waitcnt lgkmcnt(0)
	v_mul_f32_e32 v53, v81, v41
	v_fma_f32 v41, v54, s66, 0.5
	v_lshl_add_u32 v55, v86, 3, 0
	v_fma_f32 v41, v54, v41, 1.0
	ds_write_b64 v55, v[52:53] offset:36864
	v_mul_f32_e32 v41, v54, v41
	v_cmp_lt_f32_e32 vcc, s79, v54
	s_cmp_lg_u32 s101, 0
	s_cbranch_scc1 .Llruw0_14
	global_load_dwordx4 v[198:201], v[68:69], off offset:128
.Llruw0_14:
	v_mul_f32_e32 v40, 0x3fb8aa3b, v40
	v_exp_f32_e32 v40, v40
	s_movk_i32 s3, 0x1980
	v_add3_u32 v81, v94, s3, v91
	v_add_f32_e32 v50, v50, v92
	v_fma_f32 v48, v40, v40, -1.0
	v_cndmask_b32_e32 v41, v48, v41, vcc
	v_max_f32_e64 v41, -v41, 0
	v_sqrt_f32_e32 v41, v41
	ds_read_b32 v48, v81 offset:12288
	v_mul_f32_e32 v50, 0xbfb8aa3b, v50
	v_add_f32_e32 v42, v42, v93
	v_exp_f32_e32 v50, v50
	v_mul_f32_e32 v42, 0xbfb8aa3b, v42
	s_waitcnt vmcnt(0)
	v_mfma_f32_16x16x32_bf16 v[82:85], v[20:23], v[180:183], 0
	v_mul_f32_e32 v41, v95, v41
	v_exp_f32_e32 v42, v42
	s_waitcnt lgkmcnt(0)
	v_mul_f32_e32 v41, v48, v41
	v_mfma_f32_16x16x32_bf16 v[86:89], v[8:11], v[180:183], 0
	v_or_b32_e32 v56, 17, v60
	v_mad_u32_u24 v48, v56, s46, v90
	v_lshl_add_u32 v48, v48, 3, 0
	ds_write_b64 v48, v[40:41] offset:36864
	v_add_f32_e32 v40, 1.0, v50
	v_rcp_f32_e32 v41, v40
	v_add_f32_e32 v40, 1.0, v42
	v_rcp_f32_e32 v48, v40
	v_add_f32_e32 v40, v51, v92
	v_mul_f32_e32 v40, 0xbfb8aa3b, v40
	v_exp_f32_e32 v40, v40
	v_add_f32_e32 v42, v43, v93
	v_mul_f32_e32 v42, 0xbfb8aa3b, v42
	v_exp_f32_e32 v43, v42
	v_add_f32_e32 v40, 1.0, v40
	v_rcp_f32_e32 v40, v40
	s_movk_i32 s3, 0x1b00
	v_add3_u32 v50, v94, s3, v91
	ds_read_b32 v57, v50 offset:12288
	v_pk_mul_f32 v[40:41], v[40:41], s[86:87] op_sel_hi:[1,0]
	v_or_b32_e32 v51, 18, v60
	v_pk_mul_f32 v[40:41], v[66:67], v[40:41] op_sel_hi:[0,1]
	v_mul_f32_e32 v42, 0x3fb8aa3b, v41
	v_exp_f32_e32 v42, v42
	v_pk_add_f32 v[58:59], v[40:41], v[40:41]
	v_mul_f32_e32 v40, 0x3fb8aa3b, v40
	v_fma_f32 v41, v59, s66, 0.5
	v_fma_f32 v41, v59, v41, 1.0
	v_mul_f32_e32 v41, v59, v41
	v_fma_f32 v66, v42, v42, -1.0
	v_cmp_lt_f32_e32 vcc, s79, v59
	v_exp_f32_e32 v40, v40
	v_add_f32_e32 v43, 1.0, v43
	v_cndmask_b32_e32 v41, v66, v41, vcc
	v_max_f32_e64 v41, -v41, 0
	v_sqrt_f32_e32 v41, v41
	v_mad_u32_u24 v68, v51, s46, v90
	v_rcp_f32_e32 v66, v43
	v_lshl_add_u32 v59, v68, 3, 0
	v_mul_f32_e32 v41, v48, v41
	s_waitcnt lgkmcnt(0)
	v_mul_f32_e32 v43, v57, v41
	v_fma_f32 v41, v58, s66, 0.5
	v_fma_f32 v41, v58, v41, 1.0
	ds_write_b64 v59, v[42:43] offset:36864
	v_mul_f32_e32 v41, v58, v41
	v_fma_f32 v42, v40, v40, -1.0
	v_cmp_lt_f32_e32 vcc, s79, v58
	s_movk_i32 s3, 0x1c80
	v_add3_u32 v57, v94, s3, v91
	v_cndmask_b32_e32 v41, v42, v41, vcc
	v_max_f32_e64 v41, -v41, 0
	v_sqrt_f32_e32 v41, v41
	ds_read_b32 v42, v57 offset:12288
	v_or_b32_e32 v58, 19, v60
	s_waitcnt vmcnt(0)
	v_mfma_f32_16x16x32_bf16 v[82:85], v[12:15], v[194:197], v[82:85]
	v_mul_f32_e32 v41, v66, v41
	v_add_u32_e32 v43, v76, v71
	s_waitcnt lgkmcnt(0)
	v_mul_f32_e32 v41, v42, v41
	v_mad_u32_u24 v42, v58, s46, v90
	v_lshl_add_u32 v42, v42, 3, 0
	ds_write_b64 v42, v[40:41] offset:36864
	ds_read_b32 v59, v73 offset:1984
	s_waitcnt vmcnt(0)
	v_mfma_f32_16x16x32_bf16 v[82:85], v[24:27], v[198:201], v[82:85]
	ds_read_b32 v66, v73 offset:2368
	ds_read_b32 v48, v74 offset:3520
	ds_read_b32 v76, v75 offset:12352
	v_mad_u32_u24 v91, v60, s46, v72
	v_mad_i64_i32 v[64:65], s[20:21], v43, s94, v[64:65]
	s_waitcnt lgkmcnt(3)
	v_add_f32_e32 v36, v36, v59
	v_mul_f32_e32 v36, 0xbfb8aa3b, v36
	v_exp_f32_e32 v36, v36
	v_add_f32_e32 v37, v37, v59
	v_mul_f32_e32 v37, 0xbfb8aa3b, v37
	v_exp_f32_e32 v37, v37
	v_add_f32_e32 v36, 1.0, v36
	v_rcp_f32_e32 v69, v36
	s_waitcnt lgkmcnt(2)
	v_add_f32_e32 v36, v82, v66
	v_mul_f32_e32 v36, 0xbfb8aa3b, v36
	v_exp_f32_e32 v36, v36
	v_add_f32_e32 v38, v38, v59
	v_mul_f32_e32 v38, 0xbfb8aa3b, v38
	v_exp_f32_e32 v38, v38
	v_add_f32_e32 v36, 1.0, v36
	v_rcp_f32_e32 v90, v36
	v_add_f32_e32 v36, 1.0, v37
	v_rcp_f32_e32 v68, v36
	v_add_f32_e32 v36, v83, v66
	v_mul_f32_e32 v36, 0xbfb8aa3b, v36
	v_exp_f32_e32 v92, v36
	v_pk_mul_f32 v[36:37], v[68:69], s[86:87] op_sel_hi:[1,0]
	v_mfma_f32_16x16x32_bf16 v[44:47], v[4:7], v[194:197], v[86:89]
	s_waitcnt lgkmcnt(1)
	v_pk_mul_f32 v[36:37], v[48:49], v[36:37] op_sel_hi:[0,1]
	v_mul_f32_e32 v68, 0x3fb8aa3b, v37
	v_exp_f32_e32 v68, v68
	v_pk_add_f32 v[82:83], v[36:37], v[36:37]
	v_mul_f32_e32 v36, 0x3fb8aa3b, v36
	v_fma_f32 v37, v83, s66, 0.5
	v_fma_f32 v37, v83, v37, 1.0
	v_mul_f32_e32 v37, v83, v37
	v_fma_f32 v69, v68, v68, -1.0
	v_cmp_lt_f32_e32 vcc, s79, v83
	v_exp_f32_e32 v36, v36
	v_lshl_add_u32 v83, v91, 3, 0
	v_cndmask_b32_e32 v37, v69, v37, vcc
	v_max_f32_e64 v37, -v37, 0
	v_sqrt_f32_e32 v37, v37
	v_add_f32_e32 v69, 1.0, v92
	v_rcp_f32_e32 v91, v69
	v_cmp_lt_f32_e32 vcc, s79, v82
	v_mul_f32_e32 v37, v90, v37
	s_waitcnt lgkmcnt(0)
	v_mul_f32_e32 v69, v76, v37
	v_fma_f32 v37, v82, s66, 0.5
	v_fma_f32 v37, v82, v37, 1.0
	ds_write_b64 v83, v[68:69] offset:36864
	v_mul_f32_e32 v37, v82, v37
	v_fma_f32 v68, v36, v36, -1.0
	v_cndmask_b32_e32 v37, v68, v37, vcc
	v_max_f32_e64 v37, -v37, 0
	v_sqrt_f32_e32 v37, v37
	ds_read_b32 v68, v62 offset:12352
	v_add_f32_e32 v69, v84, v66
	v_mul_f32_e32 v69, 0xbfb8aa3b, v69
	v_mul_f32_e32 v37, v91, v37
	v_exp_f32_e32 v69, v69
	s_waitcnt lgkmcnt(0)
	v_mul_f32_e32 v37, v68, v37
	v_mad_u32_u24 v68, v63, s46, v72
	v_lshl_add_u32 v68, v68, 3, 0
	ds_write_b64 v68, v[36:37] offset:36864
	v_add_f32_e32 v36, 1.0, v38
	v_add_f32_e32 v38, v39, v59
	v_mul_f32_e32 v38, 0xbfb8aa3b, v38
	v_exp_f32_e32 v38, v38
	v_rcp_f32_e32 v37, v36
	v_add_f32_e32 v36, 1.0, v69
	v_rcp_f32_e32 v39, v36
	v_add_f32_e32 v36, 1.0, v38
	v_rcp_f32_e32 v36, v36
	v_add_f32_e32 v38, v85, v66
	v_mul_f32_e32 v38, 0xbfb8aa3b, v38
	v_exp_f32_e32 v83, v38
	v_pk_mul_f32 v[36:37], v[36:37], s[86:87] op_sel_hi:[1,0]
	v_mad_u32_u24 v82, v77, s46, v72
	v_pk_mul_f32 v[36:37], v[48:49], v[36:37] op_sel_hi:[0,1]
	v_mul_f32_e32 v38, 0x3fb8aa3b, v37
	v_exp_f32_e32 v38, v38
	v_pk_add_f32 v[68:69], v[36:37], v[36:37]
	ds_read_b32 v76, v61 offset:12352
	v_fma_f32 v37, v69, s66, 0.5
	v_fma_f32 v37, v69, v37, 1.0
	v_mul_f32_e32 v37, v69, v37
	v_fma_f32 v84, v38, v38, -1.0
	v_cmp_lt_f32_e32 vcc, s79, v69
	v_lshl_add_u32 v69, v82, 3, 0
	v_add_f32_e32 v82, 1.0, v83
	v_cndmask_b32_e32 v37, v84, v37, vcc
	v_max_f32_e64 v37, -v37, 0
	v_sqrt_f32_e32 v37, v37
	v_mul_f32_e32 v36, 0x3fb8aa3b, v36
	v_rcp_f32_e32 v83, v82
	v_exp_f32_e32 v82, v36
	s_cmp_lg_u32 s101, 0
	s_cbranch_scc1 .Llruw0_15
	global_load_dwordx4 v[202:205], v[64:65], off
.Llruw0_15:
	v_fma_f32 v36, v68, s66, 0.5
	v_mfma_f32_16x16x32_bf16 v[44:47], v[0:3], v[198:201], v[44:47]
	v_mul_f32_e32 v37, v39, v37
	v_fma_f32 v36, v68, v36, 1.0
	s_waitcnt lgkmcnt(0)
	v_mul_f32_e32 v39, v76, v37
	v_mul_f32_e32 v36, v68, v36
	v_fma_f32 v37, v82, v82, -1.0
	v_cmp_lt_f32_e32 vcc, s79, v68
	v_add_f32_e32 v32, v32, v59
	ds_write_b64 v69, v[38:39] offset:36864
	v_cndmask_b32_e32 v36, v37, v36, vcc
	v_max_f32_e64 v36, -v36, 0
	v_mul_f32_e32 v32, 0xbfb8aa3b, v32
	v_add_f32_e32 v44, v44, v66
	v_sqrt_f32_e32 v68, v36
	ds_read_b32 v69, v79 offset:12352
	v_exp_f32_e32 v32, v32
	v_mul_f32_e32 v44, 0xbfb8aa3b, v44
	v_add_f32_e32 v33, v33, v59
	v_exp_f32_e32 v44, v44
	v_mul_f32_e32 v33, 0xbfb8aa3b, v33
	v_exp_f32_e32 v33, v33
	s_cmp_lg_u32 s101, 0
	s_cbranch_scc1 .Llruw0_16
	global_load_dwordx4 v[206:209], v[64:65], off offset:64
.Llruw0_16:
	s_cmp_lg_u32 s101, 0
	s_cbranch_scc1 .Llruw0_17
	global_load_dwordx4 v[210:213], v[64:65], off offset:128
.Llruw0_17:
	v_mul_f32_e32 v64, v83, v68
	v_add_f32_e32 v32, 1.0, v32
	s_waitcnt lgkmcnt(0)
	v_mul_f32_e32 v83, v69, v64
	v_mad_u32_u24 v64, v80, s46, v72
	v_rcp_f32_e32 v65, v32
	v_add_f32_e32 v32, 1.0, v44
	v_lshl_add_u32 v64, v64, 3, 0
	v_rcp_f32_e32 v68, v32
	v_add_f32_e32 v32, 1.0, v33
	ds_write_b64 v64, v[82:83] offset:36864
	v_rcp_f32_e32 v64, v32
	v_add_f32_e32 v32, v45, v66
	v_mul_f32_e32 v32, 0xbfb8aa3b, v32
	v_exp_f32_e32 v45, v32
	v_pk_mul_f32 v[32:33], v[64:65], s[86:87] op_sel_hi:[1,0]
	ds_read_b32 v69, v78 offset:12352
	v_pk_mul_f32 v[32:33], v[48:49], v[32:33] op_sel_hi:[0,1]
	v_mul_f32_e32 v44, 0x3fb8aa3b, v33
	v_exp_f32_e32 v44, v44
	v_pk_add_f32 v[64:65], v[32:33], v[32:33]
	v_mul_f32_e32 v32, 0x3fb8aa3b, v32
	v_fma_f32 v33, v65, s66, 0.5
	v_fma_f32 v33, v65, v33, 1.0
	v_mul_f32_e32 v33, v65, v33
	v_fma_f32 v82, v44, v44, -1.0
	v_cmp_lt_f32_e32 vcc, s79, v65
	v_exp_f32_e32 v32, v32
	v_mad_u32_u24 v76, v49, s46, v72
	v_cndmask_b32_e32 v33, v82, v33, vcc
	v_max_f32_e64 v33, -v33, 0
	v_sqrt_f32_e32 v33, v33
	v_add_f32_e32 v45, 1.0, v45
	v_lshl_add_u32 v65, v76, 3, 0
	v_rcp_f32_e32 v76, v45
	v_mul_f32_e32 v33, v68, v33
	s_waitcnt lgkmcnt(0)
	v_mul_f32_e32 v45, v69, v33
	v_fma_f32 v33, v64, s66, 0.5
	v_fma_f32 v33, v64, v33, 1.0
	ds_write_b64 v65, v[44:45] offset:36864
	v_mul_f32_e32 v33, v64, v33
	v_fma_f32 v44, v32, v32, -1.0
	v_cmp_lt_f32_e32 vcc, s79, v64
	v_add_f32_e32 v34, v34, v59
	v_mul_f32_e32 v34, 0xbfb8aa3b, v34
	v_cndmask_b32_e32 v33, v44, v33, vcc
	v_max_f32_e64 v33, -v33, 0
	v_sqrt_f32_e32 v33, v33
	ds_read_b32 v44, v81 offset:12352
	v_exp_f32_e32 v34, v34
	v_add_f32_e32 v45, v46, v66
	v_mul_f32_e32 v33, v76, v33
	v_mul_f32_e32 v45, 0xbfb8aa3b, v45
	s_waitcnt lgkmcnt(0)
	v_mul_f32_e32 v33, v44, v33
	v_mad_u32_u24 v44, v56, s46, v72
	v_lshl_add_u32 v44, v44, 3, 0
	ds_write_b64 v44, v[32:33] offset:36864
	v_add_f32_e32 v32, 1.0, v34
	v_add_f32_e32 v34, v35, v59
	v_exp_f32_e32 v45, v45
	v_mul_f32_e32 v34, 0xbfb8aa3b, v34
	v_exp_f32_e32 v34, v34
	v_rcp_f32_e32 v33, v32
	v_add_f32_e32 v32, 1.0, v45
	v_rcp_f32_e32 v35, v32
	v_add_f32_e32 v32, 1.0, v34
	v_rcp_f32_e32 v32, v32
	v_add_f32_e32 v34, v47, v66
	v_mul_f32_e32 v34, 0xbfb8aa3b, v34
	v_exp_f32_e32 v47, v34
	v_pk_mul_f32 v[32:33], v[32:33], s[86:87] op_sel_hi:[1,0]
	ds_read_b32 v46, v50 offset:12352
	v_pk_mul_f32 v[32:33], v[48:49], v[32:33] op_sel_hi:[0,1]
	v_mul_f32_e32 v34, 0x3fb8aa3b, v33
	v_exp_f32_e32 v34, v34
	v_pk_add_f32 v[44:45], v[32:33], v[32:33]
	v_mul_f32_e32 v32, 0x3fb8aa3b, v32
	v_fma_f32 v33, v45, s66, 0.5
	v_fma_f32 v33, v45, v33, 1.0
	v_mul_f32_e32 v33, v45, v33
	v_fma_f32 v48, v34, v34, -1.0
	v_cmp_lt_f32_e32 vcc, s79, v45
	v_mad_u32_u24 v59, v51, s46, v72
	v_lshl_add_u32 v45, v59, 3, 0
	v_cndmask_b32_e32 v33, v48, v33, vcc
	v_max_f32_e64 v33, -v33, 0
	v_sqrt_f32_e32 v33, v33
	v_cmp_lt_f32_e32 vcc, s79, v44
	v_add_f32_e32 v47, 1.0, v47
	v_rcp_f32_e32 v47, v47
	v_mul_f32_e32 v33, v35, v33
	s_waitcnt lgkmcnt(0)
	v_mul_f32_e32 v35, v46, v33
	v_exp_f32_e32 v46, v32
	v_fma_f32 v32, v44, s66, 0.5
	v_fma_f32 v32, v44, v32, 1.0
	v_mul_f32_e32 v32, v44, v32
	v_fma_f32 v33, v46, v46, -1.0
	v_cndmask_b32_e32 v32, v33, v32, vcc
	ds_write_b64 v45, v[34:35] offset:36864
	v_max_f32_e64 v32, -v32, 0
	v_sqrt_f32_e32 v44, v32
	ds_read_b32 v45, v57 offset:12352
	s_waitcnt vmcnt(0)
	v_mfma_f32_16x16x32_bf16 v[32:35], v[8:11], v[202:205], 0
	v_mul_f32_e32 v8, v47, v44
	s_waitcnt lgkmcnt(0)
	v_mul_f32_e32 v47, v45, v8
	v_mad_u32_u24 v8, v58, s46, v72
	v_lshl_add_u32 v8, v8, 3, 0
	v_mfma_f32_16x16x32_bf16 v[20:23], v[20:23], v[202:205], 0
	ds_write_b64 v8, v[46:47] offset:36864
	ds_read_b32 v9, v73 offset:2048
	s_waitcnt vmcnt(0)
	v_mfma_f32_16x16x32_bf16 v[10:13], v[12:15], v[206:209], v[20:23]
	s_nop 3
	ds_read_b32 v22, v73 offset:2432
	ds_read_b32 v8, v74 offset:3584
	ds_read_b32 v23, v75 offset:12416
	s_waitcnt lgkmcnt(3)
	v_add_f32_e32 v14, v28, v9
	v_mul_f32_e32 v14, 0xbfb8aa3b, v14
	v_exp_f32_e32 v14, v14
	s_waitcnt vmcnt(0)
	v_mfma_f32_16x16x32_bf16 v[10:13], v[24:27], v[210:213], v[10:13]
	v_or_b32_e32 v24, v71, v70
	v_mad_u32_u24 v26, v60, s46, v24
	v_add_f32_e32 v14, 1.0, v14
	v_rcp_f32_e32 v15, v14
	v_add_f32_e32 v14, v29, v9
	s_waitcnt lgkmcnt(2)
	s_nop 1
	v_add_f32_e32 v10, v10, v22
	v_mul_f32_e32 v10, 0xbfb8aa3b, v10
	v_exp_f32_e32 v10, v10
	v_mul_f32_e32 v14, 0xbfb8aa3b, v14
	v_exp_f32_e32 v14, v14
	v_add_f32_e32 v12, v12, v22
	v_add_f32_e32 v10, 1.0, v10
	v_rcp_f32_e32 v25, v10
	v_add_f32_e32 v10, 1.0, v14
	v_rcp_f32_e32 v14, v10
	v_add_f32_e32 v10, v11, v22
	v_mul_f32_e32 v10, 0xbfb8aa3b, v10
	v_exp_f32_e32 v27, v10
	v_pk_mul_f32 v[10:11], v[14:15], s[86:87] op_sel_hi:[1,0]
	v_mul_f32_e32 v12, 0xbfb8aa3b, v12
	s_waitcnt lgkmcnt(1)
	v_pk_mul_f32 v[10:11], v[8:9], v[10:11] op_sel_hi:[0,1]
	v_mul_f32_e32 v14, 0x3fb8aa3b, v11
	v_exp_f32_e32 v14, v14
	v_pk_add_f32 v[20:21], v[10:11], v[10:11]
	v_mul_f32_e32 v10, 0x3fb8aa3b, v10
	v_fma_f32 v11, v21, s66, 0.5
	v_fma_f32 v11, v21, v11, 1.0
	v_mul_f32_e32 v11, v21, v11
	v_fma_f32 v15, v14, v14, -1.0
	v_cmp_lt_f32_e32 vcc, s79, v21
	v_exp_f32_e32 v10, v10
	v_lshl_add_u32 v21, v26, 3, 0
	v_cndmask_b32_e32 v11, v15, v11, vcc
	v_max_f32_e64 v11, -v11, 0
	v_sqrt_f32_e32 v11, v11
	v_add_f32_e32 v15, 1.0, v27
	v_rcp_f32_e32 v26, v15
	v_cmp_lt_f32_e32 vcc, s79, v20
	v_mul_f32_e32 v11, v25, v11
	s_waitcnt lgkmcnt(0)
	v_mul_f32_e32 v15, v23, v11
	v_fma_f32 v11, v20, s66, 0.5
	v_fma_f32 v11, v20, v11, 1.0
	ds_write_b64 v21, v[14:15] offset:36864
	v_mul_f32_e32 v11, v20, v11
	v_fma_f32 v14, v10, v10, -1.0
	v_cndmask_b32_e32 v11, v14, v11, vcc
	v_max_f32_e64 v11, -v11, 0
	v_sqrt_f32_e32 v11, v11
	ds_read_b32 v14, v62 offset:12416
	v_add_f32_e32 v15, v30, v9
	v_mul_f32_e32 v15, 0xbfb8aa3b, v15
	v_exp_f32_e32 v15, v15
	v_mul_f32_e32 v11, v26, v11
	v_exp_f32_e32 v12, v12
	s_waitcnt lgkmcnt(0)
	v_mul_f32_e32 v11, v14, v11
	v_mad_u32_u24 v14, v63, s46, v24
	v_lshl_add_u32 v14, v14, 3, 0
	ds_write_b64 v14, v[10:11] offset:36864
	v_add_f32_e32 v10, 1.0, v15
	v_rcp_f32_e32 v11, v10
	v_add_f32_e32 v10, 1.0, v12
	v_add_f32_e32 v12, v31, v9
	v_mul_f32_e32 v12, 0xbfb8aa3b, v12
	v_exp_f32_e32 v12, v12
	v_rcp_f32_e32 v20, v10
	ds_read_b32 v21, v61 offset:12416
	v_mad_u32_u24 v23, v77, s46, v24
	v_add_f32_e32 v10, 1.0, v12
	v_rcp_f32_e32 v10, v10
	v_add_f32_e32 v12, v13, v22
	v_mul_f32_e32 v12, 0xbfb8aa3b, v12
	v_exp_f32_e32 v13, v12
	v_pk_mul_f32 v[10:11], v[10:11], s[86:87] op_sel_hi:[1,0]
	v_mfma_f32_16x16x32_bf16 v[4:7], v[4:7], v[206:209], v[32:35]
	v_mul_f32_e64 v10, v8, v10
	v_mul_f32_e64 v11, v8, v11
	v_mul_f32_e32 v12, 0x3fb8aa3b, v11
	v_exp_f32_e32 v12, v12
	v_pk_add_f32 v[14:15], v[10:11], v[10:11]
	v_mul_f32_e32 v10, 0x3fb8aa3b, v10
	v_fma_f32 v11, v15, s66, 0.5
	v_fma_f32 v11, v15, v11, 1.0
	v_mul_f32_e32 v11, v15, v11
	v_fma_f32 v25, v12, v12, -1.0
	v_cmp_lt_f32_e32 vcc, s79, v15
	v_exp_f32_e32 v10, v10
	v_add_f32_e32 v13, 1.0, v13
	v_cndmask_b32_e32 v11, v25, v11, vcc
	v_max_f32_e64 v11, -v11, 0
	v_sqrt_f32_e32 v11, v11
	v_lshl_add_u32 v15, v23, 3, 0
	v_rcp_f32_e32 v23, v13
	v_cmp_lt_f32_e32 vcc, s79, v14
	v_mul_f32_e32 v11, v20, v11
	s_waitcnt lgkmcnt(0)
	v_mul_f32_e32 v13, v21, v11
	v_fma_f32 v11, v14, s66, 0.5
	v_fma_f32 v11, v14, v11, 1.0
	ds_write_b64 v15, v[12:13] offset:36864
	v_mul_f32_e32 v11, v14, v11
	v_fma_f32 v12, v10, v10, -1.0
	v_cndmask_b32_e32 v11, v12, v11, vcc
	v_max_f32_e64 v11, -v11, 0
	v_sqrt_f32_e32 v11, v11
	ds_read_b32 v12, v79 offset:12416
	v_mfma_f32_16x16x32_bf16 v[0:3], v[0:3], v[210:213], v[4:7]
	s_nop 2
	v_add_f32_e32 v5, v16, v9
	v_mul_f32_e32 v5, 0xbfb8aa3b, v5
	v_exp_f32_e32 v5, v5
	v_mul_f32_e32 v4, v23, v11
	s_waitcnt lgkmcnt(0)
	v_mul_f32_e32 v11, v12, v4
	v_mad_u32_u24 v4, v80, s46, v24
	v_lshl_add_u32 v4, v4, 3, 0
	v_add_f32_e32 v0, v0, v22
	ds_write_b64 v4, v[10:11] offset:36864
	v_add_f32_e32 v4, 1.0, v5
	v_mul_f32_e32 v0, 0xbfb8aa3b, v0
	v_rcp_f32_e32 v5, v4
	v_add_f32_e32 v4, v17, v9
	v_exp_f32_e32 v0, v0
	v_mul_f32_e32 v4, 0xbfb8aa3b, v4
	v_exp_f32_e32 v4, v4
	ds_read_b32 v11, v78 offset:12416
	v_add_f32_e32 v0, 1.0, v0
	v_rcp_f32_e32 v10, v0
	v_add_f32_e32 v0, 1.0, v4
	v_rcp_f32_e32 v4, v0
	v_add_f32_e32 v0, v1, v22
	v_mul_f32_e32 v0, 0xbfb8aa3b, v0
	v_exp_f32_e32 v13, v0
	v_pk_mul_f32 v[0:1], v[4:5], s[86:87] op_sel_hi:[1,0]
	v_mad_u32_u24 v12, v49, s46, v24
	v_pk_mul_f32 v[0:1], v[8:9], v[0:1] op_sel_hi:[0,1]
	v_mul_f32_e32 v4, 0x3fb8aa3b, v1
	v_exp_f32_e32 v4, v4
	v_pk_add_f32 v[6:7], v[0:1], v[0:1]
	v_mul_f32_e32 v0, 0x3fb8aa3b, v0
	v_fma_f32 v1, v7, s66, 0.5
	v_fma_f32 v1, v7, v1, 1.0
	v_mul_f32_e32 v1, v7, v1
	v_fma_f32 v5, v4, v4, -1.0
	v_cmp_lt_f32_e32 vcc, s79, v7
	v_exp_f32_e32 v0, v0
	v_lshl_add_u32 v7, v12, 3, 0
	v_cndmask_b32_e32 v1, v5, v1, vcc
	v_max_f32_e64 v1, -v1, 0
	v_sqrt_f32_e32 v1, v1
	v_add_f32_e32 v5, 1.0, v13
	v_rcp_f32_e32 v12, v5
	v_cmp_lt_f32_e32 vcc, s79, v6
	v_mul_f32_e32 v1, v10, v1
	s_waitcnt lgkmcnt(0)
	v_mul_f32_e32 v5, v11, v1
	v_fma_f32 v1, v6, s66, 0.5
	v_fma_f32 v1, v6, v1, 1.0
	ds_write_b64 v7, v[4:5] offset:36864
	v_mul_f32_e32 v1, v6, v1
	v_fma_f32 v4, v0, v0, -1.0
	v_cndmask_b32_e32 v1, v4, v1, vcc
	v_max_f32_e64 v1, -v1, 0
	v_sqrt_f32_e32 v1, v1
	ds_read_b32 v4, v81 offset:12416
	v_add_f32_e32 v5, v18, v9
	v_mul_f32_e32 v5, 0xbfb8aa3b, v5
	v_add_f32_e32 v2, v2, v22
	v_exp_f32_e32 v5, v5
	v_mul_f32_e32 v2, 0xbfb8aa3b, v2
	v_mul_f32_e32 v1, v12, v1
	v_exp_f32_e32 v2, v2
	s_waitcnt lgkmcnt(0)
	v_mul_f32_e32 v1, v4, v1
	v_mad_u32_u24 v4, v56, s46, v24
	v_lshl_add_u32 v4, v4, 3, 0
	ds_write_b64 v4, v[0:1] offset:36864
	v_add_f32_e32 v0, 1.0, v5
	v_rcp_f32_e32 v1, v0
	v_add_f32_e32 v0, 1.0, v2
	v_add_f32_e32 v2, v19, v9
	v_mul_f32_e32 v2, 0xbfb8aa3b, v2
	v_exp_f32_e32 v2, v2
	v_rcp_f32_e32 v6, v0
	v_mad_u32_u24 v9, v51, s46, v24
	ds_read_b32 v7, v50 offset:12416
	v_add_f32_e32 v0, 1.0, v2
	v_rcp_f32_e32 v0, v0
	v_add_f32_e32 v2, v3, v22
	v_mul_f32_e32 v2, 0xbfb8aa3b, v2
	v_exp_f32_e32 v3, v2
	v_pk_mul_f32 v[0:1], v[0:1], s[86:87] op_sel_hi:[1,0]
	v_add_f32_e32 v3, 1.0, v3
	v_pk_mul_f32 v[0:1], v[8:9], v[0:1] op_sel_hi:[0,1]
	v_mul_f32_e32 v2, 0x3fb8aa3b, v1
	v_exp_f32_e32 v2, v2
	v_pk_add_f32 v[4:5], v[0:1], v[0:1]
	v_mul_f32_e32 v0, 0x3fb8aa3b, v0
	v_fma_f32 v1, v5, s66, 0.5
	v_fma_f32 v1, v5, v1, 1.0
	v_mul_f32_e32 v1, v5, v1
	v_fma_f32 v8, v2, v2, -1.0
	v_cmp_lt_f32_e32 vcc, s79, v5
	v_exp_f32_e32 v0, v0
	v_lshl_add_u32 v5, v9, 3, 0
	v_cndmask_b32_e32 v1, v8, v1, vcc
	v_max_f32_e64 v1, -v1, 0
	v_sqrt_f32_e32 v1, v1
	v_rcp_f32_e32 v8, v3
	v_cmp_lt_f32_e32 vcc, s79, v4
	v_mul_f32_e32 v1, v6, v1
	s_waitcnt lgkmcnt(0)
	v_mul_f32_e32 v3, v7, v1
	v_fma_f32 v1, v4, s66, 0.5
	v_fma_f32 v1, v4, v1, 1.0
	ds_write_b64 v5, v[2:3] offset:36864
	v_mul_f32_e32 v1, v4, v1
	v_fma_f32 v2, v0, v0, -1.0
	v_cndmask_b32_e32 v1, v2, v1, vcc
	v_max_f32_e64 v1, -v1, 0
	v_sqrt_f32_e32 v1, v1
	ds_read_b32 v2, v57 offset:12416
	v_cmp_gt_i32_e32 vcc, s94, v67
	v_mul_f32_e32 v1, v8, v1
	s_waitcnt lgkmcnt(0)
	v_mul_f32_e32 v1, v2, v1
	v_mad_u32_u24 v2, v58, s46, v24
	v_lshl_add_u32 v2, v2, 3, 0
	ds_write_b64 v2, v[0:1] offset:36864
	s_waitcnt lgkmcnt(0)
	s_mov_b32 s101, 1
	s_barrier
	s_and_saveexec_b64 s[20:21], vcc
	s_cbranch_execz .LBB0_1067
	v_mul_hi_i32 v0, v67, s81
	v_lshrrev_b32_e32 v1, 31, v0
	v_ashrrev_i32_e32 v0, 4, v0
	v_add_u32_e32 v3, v0, v1
	v_mul_lo_u32 v0, v3, s46
	v_sub_u32_e32 v2, v67, v0
	s_mulk_i32 s38, 0x60
	s_lshl_b32 s22, s39, 9
	s_movk_i32 s3, 0x1800
	v_add_u32_e32 v0, s38, v2
	v_lshl_add_u32 v1, v3, 8, s22
	v_mad_u64_u32 v[2:3], s[22:23], v3, s3, v[2:3]
	v_lshl_add_u32 v124, v2, 3, 0
	v_add_u32_e32 v2, 0x5f, v67
	s_movk_i32 s3, 0xbf
	v_cmp_gt_u32_e32 vcc, s3, v2
	v_mov_b32_e32 v126, 0xba00
	v_mov_b32_e32 v127, 0xb700
	v_cndmask_b32_e32 v3, v126, v233, vcc
	v_mov_b32_e32 v128, 0x600
	v_mov_b32_e32 v125, 0xbd00
	v_add_u32_e32 v4, v124, v3
	v_cndmask_b32_e32 v3, v127, v128, vcc
	v_mov_b32_e32 v129, 0xb400
	v_mov_b32_e32 v130, 0x900
	v_cndmask_b32_e64 v2, v125, 0, vcc
	v_add_u32_e32 v6, v124, v3
	v_cndmask_b32_e32 v3, v129, v130, vcc
	v_add_u32_e32 v2, v124, v2
	v_add_u32_e32 v8, v124, v3
	v_mov_b32_e32 v118, 0xae00
	v_mov_b32_e32 v119, 0xf00
	ds_read_b64 v[2:3], v2 offset:36864
	ds_read_b64 v[4:5], v4 offset:36864
	ds_read_b64 v[6:7], v6 offset:36864
	ds_read_b64 v[8:9], v8 offset:36864
	v_cndmask_b32_e32 v11, v118, v119, vcc
	v_mov_b32_e32 v120, 0xab00
	v_mov_b32_e32 v121, 0x1200
	v_mov_b32_e32 v116, 0xb100
	v_mov_b32_e32 v117, 0xc00
	v_add_u32_e32 v12, v124, v11
	v_cndmask_b32_e32 v11, v120, v121, vcc
	v_mov_b32_e32 v122, 0xa800
	v_mov_b32_e32 v123, 0x1500
	v_cndmask_b32_e32 v10, v116, v117, vcc
	v_add_u32_e32 v14, v124, v11
	v_cndmask_b32_e32 v11, v122, v123, vcc
	s_waitcnt lgkmcnt(3)
	v_fma_f32 v3, 0, v2, v3
	v_add_u32_e32 v10, v124, v10
	v_add_u32_e32 v16, v124, v11
	s_waitcnt lgkmcnt(2)
	v_fma_f32 v3, v4, v3, v5
	ds_read_b64 v[10:11], v10 offset:36864
	ds_read_b64 v[12:13], v12 offset:36864
	ds_read_b64 v[14:15], v14 offset:36864
	ds_read_b64 v[16:17], v16 offset:36864
	s_waitcnt lgkmcnt(5)
	v_fma_f32 v3, v6, v3, v7
	s_waitcnt lgkmcnt(4)
	v_fma_f32 v3, v8, v3, v9
	s_waitcnt lgkmcnt(3)
	v_fma_f32 v3, v10, v3, v11
	s_waitcnt lgkmcnt(2)
	v_fma_f32 v3, v12, v3, v13
	s_waitcnt lgkmcnt(1)
	v_fma_f32 v3, v14, v3, v15
	v_mov_b32_e32 v13, 0xa500
	v_mov_b32_e32 v15, 0x1800
	s_waitcnt lgkmcnt(0)
	v_fma_f32 v3, v16, v3, v17
	v_cndmask_b32_e32 v5, v13, v15, vcc
	v_mov_b32_e32 v17, 0xa200
	v_mov_b32_e32 v106, 0x1b00
	v_mov_b32_e32 v107, 0x9f00
	v_mov_b32_e32 v108, 0x1e00
	v_mov_b32_e32 v109, 0x9c00
	v_mov_b32_e32 v110, 0x2100
	v_add_u32_e32 v5, v124, v5
	v_cndmask_b32_e32 v7, v17, v106, vcc
	v_cndmask_b32_e32 v9, v107, v108, vcc
	v_cndmask_b32_e32 v11, v109, v110, vcc
	v_add_u32_e32 v7, v124, v7
	v_add_u32_e32 v9, v124, v9
	v_add_u32_e32 v11, v124, v11
	ds_read_b64 v[18:19], v5 offset:36864
	ds_read_b64 v[20:21], v7 offset:36864
	ds_read_b64 v[22:23], v9 offset:36864
	ds_read_b64 v[24:25], v11 offset:36864
	v_mul_f32_e32 v2, v2, v4
	v_mov_b32_e32 v98, 0x9900
	v_mov_b32_e32 v99, 0x2400
	v_mul_f32_e32 v2, v2, v6
	v_cndmask_b32_e32 v5, v98, v99, vcc
	v_mov_b32_e32 v100, 0x9600
	v_mov_b32_e32 v101, 0x2700
	v_mov_b32_e32 v102, 0x9300
	v_mov_b32_e32 v103, 0x2a00
	v_mov_b32_e32 v104, 0x9000
	v_mov_b32_e32 v105, 0x2d00
	s_waitcnt lgkmcnt(3)
	v_fma_f32 v3, v18, v3, v19
	v_mul_f32_e32 v2, v2, v8
	v_add_u32_e32 v5, v124, v5
	v_cndmask_b32_e32 v7, v100, v101, vcc
	v_cndmask_b32_e32 v9, v102, v103, vcc
	v_cndmask_b32_e32 v11, v104, v105, vcc
	s_waitcnt lgkmcnt(2)
	v_fma_f32 v3, v20, v3, v21
	v_mul_f32_e32 v2, v2, v10
	v_add_u32_e32 v7, v124, v7
	v_add_u32_e32 v9, v124, v9
	v_add_u32_e32 v11, v124, v11
	ds_read_b64 v[26:27], v5 offset:36864
	ds_read_b64 v[28:29], v7 offset:36864
	ds_read_b64 v[30:31], v9 offset:36864
	ds_read_b64 v[32:33], v11 offset:36864
	s_waitcnt lgkmcnt(5)
	v_fma_f32 v3, v22, v3, v23
	v_mul_f32_e32 v2, v2, v12
	s_waitcnt lgkmcnt(4)
	v_fma_f32 v3, v24, v3, v25
	v_mul_f32_e32 v2, v2, v14
	s_waitcnt lgkmcnt(3)
	v_fma_f32 v3, v26, v3, v27
	v_mul_f32_e32 v2, v2, v16
	s_waitcnt lgkmcnt(2)
	v_fma_f32 v3, v28, v3, v29
	v_mul_f32_e32 v2, v2, v18
	s_waitcnt lgkmcnt(1)
	v_fma_f32 v3, v30, v3, v31
	v_mov_b32_e32 v19, 0x8d00
	v_mov_b32_e32 v21, 0x3000
	v_mul_f32_e32 v2, v2, v20
	s_waitcnt lgkmcnt(0)
	v_fma_f32 v3, v32, v3, v33
	v_cndmask_b32_e32 v5, v19, v21, vcc
	v_mov_b32_e32 v23, 0x8a00
	v_mov_b32_e32 v25, 0x3300
	v_mov_b32_e32 v27, 0x8700
	v_mov_b32_e32 v29, 0x3600
	v_mov_b32_e32 v31, 0x8400
	v_mov_b32_e32 v33, 0x3900
	v_mul_f32_e32 v2, v2, v22
	v_add_u32_e32 v5, v124, v5
	v_cndmask_b32_e32 v7, v23, v25, vcc
	v_cndmask_b32_e32 v9, v27, v29, vcc
	v_cndmask_b32_e32 v11, v31, v33, vcc
	v_mul_f32_e32 v2, v2, v24
	v_add_u32_e32 v7, v124, v7
	v_add_u32_e32 v9, v124, v9
	v_add_u32_e32 v11, v124, v11
	ds_read_b64 v[34:35], v5 offset:36864
	ds_read_b64 v[36:37], v7 offset:36864
	ds_read_b64 v[38:39], v9 offset:36864
	ds_read_b64 v[40:41], v11 offset:36864
	v_mul_f32_e32 v2, v2, v26
	v_mov_b32_e32 v82, 0x8100
	v_mov_b32_e32 v83, 0x3c00
	v_mul_f32_e32 v2, v2, v28
	v_cndmask_b32_e32 v5, v82, v83, vcc
	v_mov_b32_e32 v84, 0x7e00
	v_mov_b32_e32 v85, 0x3f00
	v_mov_b32_e32 v86, 0x7b00
	v_mov_b32_e32 v87, 0x4200
	v_mov_b32_e32 v88, 0x7800
	v_mov_b32_e32 v89, 0x4500
	s_waitcnt lgkmcnt(3)
	v_fma_f32 v3, v34, v3, v35
	v_mul_f32_e32 v2, v2, v30
	v_add_u32_e32 v5, v124, v5
	v_cndmask_b32_e32 v7, v84, v85, vcc
	v_cndmask_b32_e32 v9, v86, v87, vcc
	v_cndmask_b32_e32 v11, v88, v89, vcc
	s_waitcnt lgkmcnt(2)
	v_fma_f32 v3, v36, v3, v37
	v_mul_f32_e32 v2, v2, v32
	v_add_u32_e32 v7, v124, v7
	v_add_u32_e32 v9, v124, v9
	v_add_u32_e32 v11, v124, v11
	ds_read_b64 v[42:43], v5 offset:36864
	ds_read_b64 v[44:45], v7 offset:36864
	ds_read_b64 v[46:47], v9 offset:36864
	ds_read_b64 v[48:49], v11 offset:36864
	s_waitcnt lgkmcnt(5)
	v_fma_f32 v3, v38, v3, v39
	v_mul_f32_e32 v2, v2, v34
	s_waitcnt lgkmcnt(4)
	v_fma_f32 v3, v40, v3, v41
	v_mul_f32_e32 v2, v2, v36
	s_waitcnt lgkmcnt(3)
	v_fma_f32 v3, v42, v3, v43
	v_mul_f32_e32 v2, v2, v38
	s_waitcnt lgkmcnt(2)
	v_fma_f32 v3, v44, v3, v45
	v_mov_b32_e32 v35, 0x7500
	v_mov_b32_e32 v37, 0x4800
	v_mul_f32_e32 v2, v2, v40
	s_waitcnt lgkmcnt(1)
	v_fma_f32 v3, v46, v3, v47
	v_cndmask_b32_e32 v5, v35, v37, vcc
	v_mov_b32_e32 v39, 0x7200
	v_mov_b32_e32 v41, 0x4b00
	v_mov_b32_e32 v43, 0x6f00
	v_mov_b32_e32 v45, 0x4e00
	v_mov_b32_e32 v47, 0x6c00
	v_mul_f32_e32 v2, v2, v42
	v_add_u32_e32 v5, v124, v5
	v_cndmask_b32_e32 v7, v39, v41, vcc
	v_cndmask_b32_e32 v9, v43, v45, vcc
	v_cndmask_b32_e32 v11, v47, v254, vcc
	v_mul_f32_e32 v2, v2, v44
	v_add_u32_e32 v7, v124, v7
	v_add_u32_e32 v9, v124, v9
	v_add_u32_e32 v11, v124, v11
	ds_read_b64 v[50:51], v5 offset:36864
	ds_read_b64 v[52:53], v7 offset:36864
	ds_read_b64 v[54:55], v9 offset:36864
	ds_read_b64 v[56:57], v11 offset:36864
	v_mul_f32_e32 v2, v2, v46
	s_waitcnt lgkmcnt(4)
	v_fma_f32 v3, v48, v3, v49
	v_mov_b32_e32 v49, 0x6900
	v_mul_f32_e32 v2, v2, v48
	v_cndmask_b32_e32 v5, v49, v225, vcc
	v_mov_b32_e32 v66, 0x6600
	s_waitcnt lgkmcnt(3)
	v_fma_f32 v3, v50, v3, v51
	v_mul_f32_e32 v2, v2, v50
	v_add_u32_e32 v5, v124, v5
	v_cndmask_b32_e32 v7, v66, v228, vcc
	v_cndmask_b32_e32 v9, v242, v243, vcc
	v_cndmask_b32_e32 v11, v244, v246, vcc
	s_waitcnt lgkmcnt(2)
	v_fma_f32 v3, v52, v3, v53
	v_mul_f32_e32 v2, v2, v52
	v_add_u32_e32 v7, v124, v7
	v_add_u32_e32 v9, v124, v9
	v_add_u32_e32 v11, v124, v11
	ds_read_b64 v[58:59], v5 offset:36864
	ds_read_b64 v[60:61], v7 offset:36864
	ds_read_b64 v[62:63], v9 offset:36864
	ds_read_b64 v[64:65], v11 offset:36864
	s_waitcnt lgkmcnt(5)
	v_fma_f32 v3, v54, v3, v55
	v_mul_f32_e32 v2, v2, v54
	s_waitcnt lgkmcnt(4)
	v_fma_f32 v3, v56, v3, v57
	v_mul_f32_e32 v2, v2, v56
	s_waitcnt lgkmcnt(3)
	v_fma_f32 v3, v58, v3, v59
	v_cndmask_b32_e32 v5, v246, v244, vcc
	v_mul_f32_e32 v2, v2, v58
	s_waitcnt lgkmcnt(2)
	v_fma_f32 v3, v60, v3, v61
	v_add_u32_e32 v5, v124, v5
	v_cndmask_b32_e32 v7, v243, v242, vcc
	v_cndmask_b32_e32 v9, v228, v66, vcc
	v_cndmask_b32_e32 v11, v225, v49, vcc
	v_mul_f32_e32 v2, v2, v60
	s_waitcnt lgkmcnt(1)
	v_fma_f32 v3, v62, v3, v63
	v_add_u32_e32 v7, v124, v7
	v_add_u32_e32 v9, v124, v9
	v_add_u32_e32 v11, v124, v11
	ds_read_b64 v[66:67], v5 offset:36864
	ds_read_b64 v[68:69], v7 offset:36864
	ds_read_b64 v[70:71], v9 offset:36864
	ds_read_b64 v[72:73], v11 offset:36864
	v_mul_f32_e32 v2, v2, v62
	s_waitcnt lgkmcnt(4)
	v_fma_f32 v3, v64, v3, v65
	v_mul_f32_e32 v2, v2, v64
	v_cndmask_b32_e32 v5, v254, v47, vcc
	s_waitcnt lgkmcnt(3)
	v_fma_f32 v3, v66, v3, v67
	v_mul_f32_e32 v2, v2, v66
	v_add_u32_e32 v5, v124, v5
	v_cndmask_b32_e32 v7, v45, v43, vcc
	v_cndmask_b32_e32 v9, v41, v39, vcc
	v_cndmask_b32_e32 v11, v37, v35, vcc
	s_waitcnt lgkmcnt(2)
	v_fma_f32 v3, v68, v3, v69
	v_mul_f32_e32 v2, v2, v68
	v_add_u32_e32 v7, v124, v7
	v_add_u32_e32 v9, v124, v9
	v_add_u32_e32 v11, v124, v11
	ds_read_b64 v[74:75], v5 offset:36864
	ds_read_b64 v[76:77], v7 offset:36864
	ds_read_b64 v[78:79], v9 offset:36864
	ds_read_b64 v[80:81], v11 offset:36864
	s_waitcnt lgkmcnt(5)
	v_fma_f32 v3, v70, v3, v71
	v_mul_f32_e32 v2, v2, v70
	s_waitcnt lgkmcnt(4)
	v_fma_f32 v3, v72, v3, v73
	v_mul_f32_e32 v2, v2, v72
	s_waitcnt lgkmcnt(3)
	v_fma_f32 v3, v74, v3, v75
	v_cndmask_b32_e32 v5, v89, v88, vcc
	v_mul_f32_e32 v2, v2, v74
	s_waitcnt lgkmcnt(2)
	v_fma_f32 v3, v76, v3, v77
	v_add_u32_e32 v5, v124, v5
	v_cndmask_b32_e32 v7, v87, v86, vcc
	v_cndmask_b32_e32 v9, v85, v84, vcc
	v_cndmask_b32_e32 v11, v83, v82, vcc
	v_mul_f32_e32 v2, v2, v76
	s_waitcnt lgkmcnt(1)
	v_fma_f32 v3, v78, v3, v79
	v_add_u32_e32 v7, v124, v7
	v_add_u32_e32 v9, v124, v9
	v_add_u32_e32 v11, v124, v11
	ds_read_b64 v[82:83], v5 offset:36864
	ds_read_b64 v[84:85], v7 offset:36864
	ds_read_b64 v[86:87], v9 offset:36864
	ds_read_b64 v[88:89], v11 offset:36864
	v_mul_f32_e32 v2, v2, v78
	s_waitcnt lgkmcnt(4)
	v_fma_f32 v3, v80, v3, v81
	v_mul_f32_e32 v2, v2, v80
	v_cndmask_b32_e32 v5, v33, v31, vcc
	s_waitcnt lgkmcnt(3)
	v_fma_f32 v3, v82, v3, v83
	v_mul_f32_e32 v2, v2, v82
	v_add_u32_e32 v5, v124, v5
	v_cndmask_b32_e32 v7, v29, v27, vcc
	v_cndmask_b32_e32 v9, v25, v23, vcc
	v_cndmask_b32_e32 v11, v21, v19, vcc
	s_waitcnt lgkmcnt(2)
	v_fma_f32 v3, v84, v3, v85
	v_mul_f32_e32 v2, v2, v84
	v_add_u32_e32 v7, v124, v7
	v_add_u32_e32 v9, v124, v9
	v_add_u32_e32 v11, v124, v11
	ds_read_b64 v[90:91], v5 offset:36864
	ds_read_b64 v[92:93], v7 offset:36864
	ds_read_b64 v[94:95], v9 offset:36864
	ds_read_b64 v[96:97], v11 offset:36864
	s_waitcnt lgkmcnt(5)
	v_fma_f32 v3, v86, v3, v87
	v_mul_f32_e32 v2, v2, v86
	s_waitcnt lgkmcnt(4)
	v_fma_f32 v3, v88, v3, v89
	v_mul_f32_e32 v2, v2, v88
	s_waitcnt lgkmcnt(3)
	v_fma_f32 v3, v90, v3, v91
	v_cndmask_b32_e32 v5, v105, v104, vcc
	v_mul_f32_e32 v2, v2, v90
	s_waitcnt lgkmcnt(2)
	v_fma_f32 v3, v92, v3, v93
	v_add_u32_e32 v5, v124, v5
	v_cndmask_b32_e32 v7, v103, v102, vcc
	v_cndmask_b32_e32 v9, v101, v100, vcc
	v_cndmask_b32_e32 v11, v99, v98, vcc
	v_mul_f32_e32 v2, v2, v92
	s_waitcnt lgkmcnt(1)
	v_fma_f32 v3, v94, v3, v95
	v_add_u32_e32 v7, v124, v7
	v_add_u32_e32 v9, v124, v9
	v_add_u32_e32 v11, v124, v11
	ds_read_b64 v[98:99], v5 offset:36864
	ds_read_b64 v[100:101], v7 offset:36864
	ds_read_b64 v[102:103], v9 offset:36864
	ds_read_b64 v[104:105], v11 offset:36864
	v_mul_f32_e32 v2, v2, v94
	s_waitcnt lgkmcnt(4)
	v_fma_f32 v3, v96, v3, v97
	v_mul_f32_e32 v2, v2, v96
	v_cndmask_b32_e32 v5, v110, v109, vcc
	s_waitcnt lgkmcnt(3)
	v_fma_f32 v3, v98, v3, v99
	v_mul_f32_e32 v2, v2, v98
	v_add_u32_e32 v5, v124, v5
	v_cndmask_b32_e32 v7, v108, v107, vcc
	v_cndmask_b32_e32 v9, v106, v17, vcc
	v_cndmask_b32_e32 v11, v15, v13, vcc
	s_waitcnt lgkmcnt(2)
	v_fma_f32 v3, v100, v3, v101
	v_mul_f32_e32 v2, v2, v100
	v_add_u32_e32 v7, v124, v7
	v_add_u32_e32 v9, v124, v9
	v_add_u32_e32 v11, v124, v11
	ds_read_b64 v[106:107], v5 offset:36864
	ds_read_b64 v[108:109], v7 offset:36864
	ds_read_b64 v[110:111], v9 offset:36864
	ds_read_b64 v[114:115], v11 offset:36864
	s_waitcnt lgkmcnt(5)
	v_fma_f32 v3, v102, v3, v103
	v_mul_f32_e32 v2, v2, v102
	s_waitcnt lgkmcnt(4)
	v_fma_f32 v3, v104, v3, v105
	v_mul_f32_e32 v2, v2, v104
	s_waitcnt lgkmcnt(3)
	v_fma_f32 v3, v106, v3, v107
	v_cndmask_b32_e32 v5, v123, v122, vcc
	v_mul_f32_e32 v2, v2, v106
	s_waitcnt lgkmcnt(2)
	v_fma_f32 v3, v108, v3, v109
	v_add_u32_e32 v5, v124, v5
	v_cndmask_b32_e32 v7, v121, v120, vcc
	v_cndmask_b32_e32 v9, v119, v118, vcc
	v_cndmask_b32_e32 v11, v117, v116, vcc
	v_mul_f32_e32 v2, v2, v108
	s_waitcnt lgkmcnt(1)
	v_fma_f32 v3, v110, v3, v111
	v_add_u32_e32 v7, v124, v7
	v_add_u32_e32 v9, v124, v9
	v_add_u32_e32 v11, v124, v11
	ds_read_b64 v[116:117], v5 offset:36864
	ds_read_b64 v[118:119], v7 offset:36864
	ds_read_b64 v[120:121], v9 offset:36864
	ds_read_b64 v[122:123], v11 offset:36864
	v_mul_f32_e32 v2, v2, v110
	s_waitcnt lgkmcnt(4)
	v_fma_f32 v3, v114, v3, v115
	v_mul_f32_e32 v2, v2, v114
	v_cndmask_b32_e32 v5, v130, v129, vcc
	s_waitcnt lgkmcnt(3)
	v_fma_f32 v3, v116, v3, v117
	v_mul_f32_e32 v2, v2, v116
	v_add_u32_e32 v5, v124, v5
	v_cndmask_b32_e32 v7, v128, v127, vcc
	v_cndmask_b32_e32 v9, v233, v126, vcc
	v_cndmask_b32_e32 v11, 0, v125, vcc
	s_waitcnt lgkmcnt(2)
	v_fma_f32 v3, v118, v3, v119
	v_mul_f32_e32 v2, v2, v118
	v_add_u32_e32 v7, v124, v7
	v_add_u32_e32 v9, v124, v9
	v_add_u32_e32 v11, v124, v11
	ds_read_b64 v[124:125], v5 offset:36864
	ds_read_b64 v[126:127], v7 offset:36864
	ds_read_b64 v[128:129], v9 offset:36864
	ds_read_b64 v[130:131], v11 offset:36864
	s_waitcnt lgkmcnt(5)
	v_fma_f32 v3, v120, v3, v121
	v_mul_f32_e32 v2, v2, v120
	s_waitcnt lgkmcnt(4)
	v_fma_f32 v3, v122, v3, v123
	v_mul_f32_e32 v2, v2, v122
	v_or_b32_e32 v112, s25, v1
	v_ashrrev_i32_e32 v1, 31, v0
	s_waitcnt lgkmcnt(3)
	v_fma_f32 v3, v124, v3, v125
	v_mul_f32_e32 v2, v2, v124
	s_waitcnt lgkmcnt(2)
	v_fma_f32 v3, v126, v3, v127
	v_mul_f32_e32 v2, v2, v126
	v_mad_i64_i32 v[0:1], s[22:23], v112, s54, v[0:1]
	s_waitcnt lgkmcnt(1)
	v_fma_f32 v3, v128, v3, v129
	v_mul_f32_e32 v2, v2, v128
	v_lshlrev_b64 v[0:1], 2, v[0:1]
	s_waitcnt lgkmcnt(0)
	v_fma_f32 v5, v130, v3, v131
	v_mul_f32_e32 v4, v2, v130
	v_lshl_add_u64 v[2:3], s[18:19], 0, v[0:1]
	v_add_co_u32_e32 v2, vcc, 0x600000, v2
	v_lshl_add_u64 v[0:1], s[6:7], 0, v[0:1]
	s_nop 0
	v_addc_co_u32_e32 v3, vcc, 0, v3, vcc
	v_add_co_u32_e32 v0, vcc, 0x300000, v0
	global_store_dword v[2:3], v5, off
	s_nop 0
	v_addc_co_u32_e32 v1, vcc, 0, v1, vcc
	global_store_dword v[0:1], v4, off
	s_branch .LBB0_1067

.LBB0_1214:
	s_and_b32 s30, s24, 7
	s_and_b32 s39, s25, 7
	s_mulk_i32 s30, 0x60
	s_cmp_eq_u32 s39, s36
	s_cbranch_scc1 .LBB0_1236
	s_mov_b32 s101, 0
	v_mov_b32_e32 v0, v224
	s_movk_i32 s3, 0x420
	s_barrier
	s_nop 0
	v_cmp_gt_i32_e32 vcc, s3, v0
	s_and_saveexec_b64 s[6:7], vcc
	s_cbranch_execz .LBB0_1235
	v_max_i32_e32 v1, 0x220, v0
	v_sub_u32_e32 v1, v1, v0
	v_add_u32_e32 v1, 0x1ff, v1
	s_movk_i32 s3, 0x1ff
	s_mul_i32 s31, s39, 0x60
	v_cmp_lt_u32_e32 vcc, s3, v1
	s_mov_b64 s[4:5], -1
	s_and_saveexec_b64 s[18:19], vcc
	s_cbranch_execz .LBB0_1220
	v_lshrrev_b32_e32 v1, 9, v1
	s_waitcnt vmcnt(1)
	v_add_u32_e32 v4, 1, v1
	s_add_i32 s22, s31, 0xfffffe80
	s_waitcnt vmcnt(0)
	v_and_b32_e32 v5, 0xfffffe, v4
	v_add_u32_e32 v1, 0x200, v0
	v_readlane_b32 s3, v255, 26
	s_mov_b32 s23, s31
	s_mov_b32 s34, s22
	v_lshl_add_u32 v6, v0, 2, s3
	s_mov_b64 s[20:21], 0
	v_mov_b32_e32 v7, v5
	v_mov_b64_e32 v[2:3], v[0:1]

.LBB0_1247:
	s_or_b64 exec, exec, s[22:23]
	v_bfe_u32 v92, v65, 6, 1
	v_lshl_or_b32 v0, v92, 4, s39
	v_and_b32_e32 v69, 15, v65
	v_bfe_u32 v68, v65, 4, 2
	v_mul_u32_u24_e32 v0, 0x60, v0
	v_lshlrev_b32_e32 v112, 4, v68
	v_lshrrev_b32_e32 v76, 8, v65
	v_or_b32_e32 v34, v0, v69
	v_lshl_add_u64 v[66:67], s[12:13], 0, v[112:113]
	v_mad_i32_i24 v0, v76, 48, v34
	v_mad_i64_i32 v[70:71], s[22:23], v0, s94, v[66:67]
	s_waitcnt lgkmcnt(0)
	s_barrier
	s_cmp_lg_u32 s101, 0
	s_cbranch_scc1 .Llruw1_0
	global_load_dwordx4 v[132:135], v[70:71], off
.Llruw1_0:
	s_waitcnt vmcnt(1)
	v_lshlrev_b32_e32 v4, 2, v65
	v_bfe_u32 v93, v65, 7, 1
	s_waitcnt vmcnt(0)
	v_lshlrev_b32_e32 v5, 6, v69
	v_and_b32_e32 v4, 32, v4
	v_mul_u32_u24_e32 v6, 0x1800, v93
	v_bitop3_b32 v4, v112, v4, v5 bitop3:0x36
	v_add3_u32 v94, 0, v4, v6
	ds_read_b128 v[20:23], v94
	ds_read_b128 v[8:11], v94 offset:3072
	v_mad_i32_i24 v73, v76, 48, 16
	v_add_u32_e32 v24, v34, v73
	v_mad_i64_i32 v[32:33], s[22:23], v24, s94, v[66:67]
	s_cmp_lg_u32 s101, 0
	s_cbranch_scc1 .Llruw1_1
	global_load_dwordx4 v[136:139], v[70:71], off offset:64
.Llruw1_1:
	v_mad_i32_i24 v72, v76, 48, 32
	v_add_u32_e32 v35, v34, v72
	v_mad_i64_i32 v[74:75], s[22:23], v35, s94, v[66:67]
	v_add_u32_e32 v77, 0x300, v34
	v_mad_i32_i24 v34, v76, 48, v77
	v_mad_i64_i32 v[90:91], s[22:23], v34, s94, v[66:67]
	ds_read_b128 v[12:15], v94 offset:1024
	v_lshlrev_b32_e32 v68, 2, v68
	v_readlane_b32 s3, v255, 27
	s_waitcnt vmcnt(0) lgkmcnt(2)
	v_mfma_f32_16x16x32_bf16 v[4:7], v[20:23], v[132:135], 0
	s_cmp_lg_u32 s101, 0
	s_cbranch_scc1 .Llruw1_2
	global_load_dwordx4 v[140:143], v[74:75], off offset:64

.Llruw1_5:
	s_waitcnt vmcnt(0)
	v_mfma_f32_16x16x32_bf16 v[78:81], v[20:23], v[152:155], 0
	v_mfma_f32_16x16x32_bf16 v[82:85], v[8:11], v[152:155], 0
	ds_read_b128 v[4:7], v94 offset:4096
	ds_read_b128 v[0:3], v94 offset:5120
	s_waitcnt lgkmcnt(1)
	v_mfma_f32_16x16x32_bf16 v[48:51], v[4:7], v[136:139], v[24:27]
	s_cmp_lg_u32 s101, 0
	s_cbranch_scc1 .Llruw1_6
	global_load_dwordx4 v[156:159], v[32:33], off offset:64

.Llruw1_9:
	v_mfma_f32_16x16x32_bf16 v[36:39], v[12:15], v[156:159], v[28:31]
	v_mfma_f32_16x16x32_bf16 v[16:19], v[4:7], v[140:143], v[60:63]
	v_mfma_f32_16x16x32_bf16 v[28:31], v[12:15], v[140:143], v[52:55]
	s_waitcnt vmcnt(0)
	v_mfma_f32_16x16x32_bf16 v[60:63], v[12:15], v[164:167], v[78:81]
	s_nop 2
	s_cmp_lg_u32 s101, 0
	s_cbranch_scc1 .Llruw1_10
	global_load_dwordx4 v[172:175], v[70:71], off offset:128
.Llruw1_10:
	v_mfma_f32_16x16x32_bf16 v[44:47], v[4:7], v[164:167], v[82:85]
	ds_read_b128 v[24:27], v94 offset:2048
	s_nop 1
	s_cmp_lg_u32 s101, 0
	s_cbranch_scc1 .Llruw1_11
	global_load_dwordx4 v[176:179], v[74:75], off offset:128
.Llruw1_11:
	v_mul_i32_i24_e32 v70, 48, v76
	v_mul_u32_u24_e32 v71, 0x300, v92
	v_mul_u32_u24_e32 v75, 0x180, v92
	s_waitcnt lgkmcnt(0)
	v_mfma_f32_16x16x32_bf16 v[36:39], v[24:27], v[160:163], v[36:39]
	v_mfma_f32_16x16x32_bf16 v[32:35], v[0:3], v[160:163], v[56:59]
	s_nop 2
	v_add_u32_e32 v56, v77, v73
	v_or_b32_e32 v73, v73, v69
	s_waitcnt vmcnt(0)
	v_mfma_f32_16x16x32_bf16 v[52:55], v[24:27], v[172:175], v[86:89]
	s_nop 2
	v_lshl_or_b32 v86, v93, 5, v68
	v_or_b32_e32 v93, v70, v69
	v_lshlrev_b32_e32 v68, 2, v93
	v_mfma_f32_16x16x32_bf16 v[48:51], v[0:3], v[172:175], v[48:51]
	v_add3_u32 v74, s3, v71, v68
	v_add_u32_e32 v94, 0, v68
	v_add3_u32 v75, s3, v75, v68
	v_mfma_f32_16x16x32_bf16 v[78:81], v[24:27], v[168:171], v[60:63]
	v_mad_u32_u24 v76, v86, s47, v94
	v_mul_u32_u24_e32 v96, 0x180, v86
	v_mad_i64_i32 v[70:71], s[22:23], v56, s94, v[66:67]
	s_waitcnt vmcnt(0)
	v_mfma_f32_16x16x32_bf16 v[28:31], v[24:27], v[176:179], v[28:31]
	s_movk_i32 s3, 0x480
	v_mfma_f32_16x16x32_bf16 v[16:19], v[0:3], v[176:179], v[16:19]
	ds_read_b32 v83, v74 offset:1920
	ds_read_b32 v95, v74 offset:2304
	ds_read_b32 v68, v75 offset:3456
	ds_read_b32 v82, v76 offset:12288
	s_cmp_lg_u32 s101, 0
	s_cbranch_scc1 .Llruw1_12
	global_load_dwordx4 v[180:183], v[70:71], off
.Llruw1_12:
	s_waitcnt lgkmcnt(3)
	v_add_f32_e32 v52, v52, v83
	v_mul_f32_e32 v52, 0xbfb8aa3b, v52
	s_waitcnt lgkmcnt(2)
	v_add_f32_e32 v60, v78, v95
	v_add_f32_e32 v53, v53, v83
	v_exp_f32_e32 v52, v52
	v_mul_f32_e32 v60, 0xbfb8aa3b, v60
	v_mul_f32_e32 v53, 0xbfb8aa3b, v53
	v_exp_f32_e32 v60, v60
	v_exp_f32_e32 v61, v53
	v_add_f32_e32 v52, 1.0, v52
	v_rcp_f32_e32 v53, v52
	v_add_f32_e32 v52, 1.0, v60
	v_rcp_f32_e32 v63, v52
	v_add_f32_e32 v52, 1.0, v61
	v_rcp_f32_e32 v52, v52
	v_add_f32_e32 v61, v79, v95
	v_lshl_or_b32 v60, v92, 6, v86
	v_mul_f32_e32 v61, 0xbfb8aa3b, v61
	v_pk_mul_f32 v[52:53], v[52:53], s[86:87] op_sel_hi:[1,0]
	v_mad_u32_u24 v84, v60, s46, v93
	s_waitcnt lgkmcnt(1)
	v_pk_mul_f32 v[52:53], v[68:69], v[52:53] op_sel_hi:[0,1]
	v_mul_f32_e32 v62, 0x3fb8aa3b, v53
	v_exp_f32_e32 v62, v62
	v_pk_add_f32 v[78:79], v[52:53], v[52:53]
	v_mul_f32_e32 v52, 0x3fb8aa3b, v52
	v_fma_f32 v53, v79, s66, 0.5
	v_fma_f32 v53, v79, v53, 1.0
	v_mul_f32_e32 v53, v79, v53
	v_fma_f32 v85, v62, v62, -1.0
	v_cmp_lt_f32_e32 vcc, s79, v79
	v_exp_f32_e32 v52, v52
	v_exp_f32_e32 v61, v61
	v_cndmask_b32_e32 v53, v85, v53, vcc
	v_max_f32_e64 v53, -v53, 0
	v_sqrt_f32_e32 v53, v53
	v_lshl_add_u32 v79, v84, 3, 0
	v_cmp_lt_f32_e32 vcc, s79, v78
	v_add_f32_e32 v61, 1.0, v61
	v_mul_f32_e32 v53, v63, v53
	s_waitcnt lgkmcnt(0)
	v_mul_f32_e32 v63, v82, v53
	v_fma_f32 v53, v78, s66, 0.5
	v_fma_f32 v53, v78, v53, 1.0
	ds_write_b64 v79, v[62:63] offset:36864
	v_mul_f32_e32 v53, v78, v53
	v_fma_f32 v62, v52, v52, -1.0
	v_cndmask_b32_e32 v53, v62, v53, vcc
	v_or_b32_e32 v62, 0x180, v96
	v_max_f32_e64 v53, -v53, 0
	v_add_u32_e32 v62, v94, v62
	v_rcp_f32_e32 v61, v61
	v_sqrt_f32_e32 v53, v53
	ds_read_b32 v63, v62 offset:12288
	v_mfma_f32_16x16x32_bf16 v[40:43], v[0:3], v[168:171], v[44:47]
	v_or_b32_e32 v78, 2, v60
	v_add_f32_e32 v48, v48, v83
	v_mul_f32_e32 v48, 0xbfb8aa3b, v48
	v_add_f32_e32 v45, v54, v83
	v_mul_f32_e32 v45, 0xbfb8aa3b, v45
	v_add_f32_e32 v46, v80, v95
	v_mul_f32_e32 v44, v61, v53
	v_exp_f32_e32 v45, v45
	v_mul_f32_e32 v46, 0xbfb8aa3b, v46
	s_waitcnt lgkmcnt(0)
	v_mul_f32_e32 v53, v63, v44
	v_or_b32_e32 v63, 1, v60
	v_exp_f32_e32 v46, v46
	v_mad_u32_u24 v44, v63, s46, v93
	v_lshl_add_u32 v44, v44, 3, 0
	ds_write_b64 v44, v[52:53] offset:36864
	v_add_f32_e32 v44, 1.0, v45
	v_rcp_f32_e32 v45, v44
	v_add_f32_e32 v44, 1.0, v46
	v_rcp_f32_e32 v47, v44
	v_add_f32_e32 v44, v55, v83
	v_mul_f32_e32 v44, 0xbfb8aa3b, v44
	v_exp_f32_e32 v44, v44
	v_add_f32_e32 v46, v81, v95
	v_mul_f32_e32 v46, 0xbfb8aa3b, v46
	v_exp_f32_e32 v79, v46
	v_add_f32_e32 v44, 1.0, v44
	v_rcp_f32_e32 v44, v44
	v_add3_u32 v61, v96, s54, v94
	ds_read_b32 v54, v61 offset:12288
	v_mad_u32_u24 v55, v78, s46, v93
	v_pk_mul_f32 v[44:45], v[44:45], s[86:87] op_sel_hi:[1,0]
	v_add_f32_e32 v40, v40, v95
	v_pk_mul_f32 v[44:45], v[68:69], v[44:45] op_sel_hi:[0,1]
	v_mul_f32_e32 v46, 0x3fb8aa3b, v45
	v_exp_f32_e32 v46, v46
	v_pk_add_f32 v[52:53], v[44:45], v[44:45]
	v_mul_f32_e32 v44, 0x3fb8aa3b, v44
	v_fma_f32 v45, v53, s66, 0.5
	v_fma_f32 v45, v53, v45, 1.0
	v_mul_f32_e32 v45, v53, v45
	v_fma_f32 v80, v46, v46, -1.0
	v_cmp_lt_f32_e32 vcc, s79, v53
	v_lshl_add_u32 v53, v55, 3, 0
	v_add_f32_e32 v55, 1.0, v79
	v_cndmask_b32_e32 v45, v80, v45, vcc
	v_max_f32_e64 v45, -v45, 0
	v_sqrt_f32_e32 v45, v45
	v_cmp_lt_f32_e32 vcc, s79, v52
	v_add3_u32 v80, v96, s3, v94
	v_mul_f32_e32 v40, 0xbfb8aa3b, v40
	v_mul_f32_e32 v45, v47, v45
	s_waitcnt lgkmcnt(0)
	v_mul_f32_e32 v47, v54, v45
	v_exp_f32_e32 v54, v44
	v_fma_f32 v44, v52, s66, 0.5
	v_fma_f32 v44, v52, v44, 1.0
	v_mul_f32_e32 v44, v52, v44
	v_fma_f32 v45, v54, v54, -1.0
	v_cndmask_b32_e32 v44, v45, v44, vcc
	ds_write_b64 v53, v[46:47] offset:36864
	v_max_f32_e64 v44, -v44, 0
	v_rcp_f32_e32 v55, v55
	v_sqrt_f32_e32 v52, v44
	ds_read_b32 v53, v80 offset:12288
	v_exp_f32_e32 v48, v48
	v_exp_f32_e32 v40, v40
	v_mul_f32_e32 v52, v55, v52
	v_or_b32_e32 v81, 3, v60
	v_add_f32_e32 v48, 1.0, v48
	v_add_f32_e32 v40, 1.0, v40
	s_waitcnt lgkmcnt(0)
	v_mul_f32_e32 v55, v53, v52
	v_rcp_f32_e32 v53, v48
	v_rcp_f32_e32 v48, v40
	v_add_f32_e32 v40, v49, v83
	v_mul_f32_e32 v40, 0xbfb8aa3b, v40
	v_exp_f32_e32 v40, v40
	v_mad_u32_u24 v52, v81, s46, v93
	v_lshl_add_u32 v52, v52, 3, 0
	ds_write_b64 v52, v[54:55] offset:36864
	v_add_f32_e32 v40, 1.0, v40
	v_rcp_f32_e32 v52, v40
	v_add_f32_e32 v40, v41, v95
	v_mul_f32_e32 v40, 0xbfb8aa3b, v40
	v_exp_f32_e32 v89, v40
	v_pk_mul_f32 v[40:41], v[52:53], s[86:87] op_sel_hi:[1,0]
	s_movk_i32 s3, 0x1800
	v_pk_mul_f32 v[40:41], v[68:69], v[40:41] op_sel_hi:[0,1]
	v_mul_f32_e32 v52, 0x3fb8aa3b, v41
	v_exp_f32_e32 v52, v52
	v_pk_add_f32 v[54:55], v[40:41], v[40:41]
	v_add3_u32 v79, v96, s3, v94
	v_fma_f32 v41, v55, s66, 0.5
	v_fma_f32 v41, v55, v41, 1.0
	v_mul_f32_e32 v41, v55, v41
	v_fma_f32 v53, v52, v52, -1.0
	v_cmp_lt_f32_e32 vcc, s79, v55
	ds_read_b32 v82, v79 offset:12288
	s_cmp_lg_u32 s101, 0
	s_cbranch_scc1 .Llruw1_13
	global_load_dwordx4 v[194:197], v[70:71], off offset:64
.Llruw1_13:
	v_cndmask_b32_e32 v41, v53, v41, vcc
	v_max_f32_e64 v41, -v41, 0
	v_sqrt_f32_e32 v41, v41
	v_or_b32_e32 v49, 16, v60
	v_add_f32_e32 v53, 1.0, v89
	v_mad_u32_u24 v88, v49, s46, v93
	v_mul_f32_e32 v41, v48, v41
	v_rcp_f32_e32 v92, v53
	s_waitcnt lgkmcnt(0)
	v_mul_f32_e32 v53, v82, v41
	v_fma_f32 v41, v54, s66, 0.5
	v_lshl_add_u32 v55, v88, 3, 0
	v_fma_f32 v41, v54, v41, 1.0
	ds_write_b64 v55, v[52:53] offset:36864
	v_mul_f32_e32 v41, v54, v41
	v_cmp_lt_f32_e32 vcc, s79, v54
	s_cmp_lg_u32 s101, 0
	s_cbranch_scc1 .Llruw1_14
	global_load_dwordx4 v[198:201], v[70:71], off offset:128
.Llruw1_14:
	v_mul_f32_e32 v40, 0x3fb8aa3b, v40
	v_exp_f32_e32 v40, v40
	s_movk_i32 s3, 0x1980
	v_add3_u32 v82, v96, s3, v94
	v_add_f32_e32 v50, v50, v83
	v_fma_f32 v48, v40, v40, -1.0
	v_cndmask_b32_e32 v41, v48, v41, vcc
	v_max_f32_e64 v41, -v41, 0
	v_sqrt_f32_e32 v41, v41
	ds_read_b32 v48, v82 offset:12288
	v_mul_f32_e32 v50, 0xbfb8aa3b, v50
	v_add_f32_e32 v42, v42, v95
	v_exp_f32_e32 v50, v50
	v_mul_f32_e32 v42, 0xbfb8aa3b, v42
	s_waitcnt vmcnt(0)
	v_mfma_f32_16x16x32_bf16 v[84:87], v[20:23], v[180:183], 0
	v_mul_f32_e32 v41, v92, v41
	v_exp_f32_e32 v42, v42
	s_waitcnt lgkmcnt(0)
	v_mul_f32_e32 v41, v48, v41
	v_mfma_f32_16x16x32_bf16 v[88:91], v[8:11], v[180:183], 0
	v_or_b32_e32 v56, 17, v60
	v_mad_u32_u24 v48, v56, s46, v93
	v_lshl_add_u32 v48, v48, 3, 0
	ds_write_b64 v48, v[40:41] offset:36864
	v_add_f32_e32 v40, 1.0, v50
	v_rcp_f32_e32 v41, v40
	v_add_f32_e32 v40, 1.0, v42
	v_rcp_f32_e32 v48, v40
	v_add_f32_e32 v40, v51, v83
	v_mul_f32_e32 v40, 0xbfb8aa3b, v40
	v_exp_f32_e32 v40, v40
	v_add_f32_e32 v42, v43, v95
	v_mul_f32_e32 v42, 0xbfb8aa3b, v42
	v_exp_f32_e32 v43, v42
	v_add_f32_e32 v40, 1.0, v40
	v_rcp_f32_e32 v40, v40
	s_movk_i32 s3, 0x1b00
	v_add3_u32 v50, v96, s3, v94
	ds_read_b32 v57, v50 offset:12288
	v_pk_mul_f32 v[40:41], v[40:41], s[86:87] op_sel_hi:[1,0]
	v_or_b32_e32 v51, 18, v60
	v_pk_mul_f32 v[40:41], v[68:69], v[40:41] op_sel_hi:[0,1]
	v_mul_f32_e32 v42, 0x3fb8aa3b, v41
	v_exp_f32_e32 v42, v42
	v_pk_add_f32 v[58:59], v[40:41], v[40:41]
	v_mul_f32_e32 v40, 0x3fb8aa3b, v40
	v_fma_f32 v41, v59, s66, 0.5
	v_fma_f32 v41, v59, v41, 1.0
	v_mul_f32_e32 v41, v59, v41
	v_fma_f32 v68, v42, v42, -1.0
	v_cmp_lt_f32_e32 vcc, s79, v59
	v_exp_f32_e32 v40, v40
	v_add_f32_e32 v43, 1.0, v43
	v_cndmask_b32_e32 v41, v68, v41, vcc
	v_max_f32_e64 v41, -v41, 0
	v_sqrt_f32_e32 v41, v41
	v_mad_u32_u24 v70, v51, s46, v93
	v_rcp_f32_e32 v68, v43
	v_lshl_add_u32 v59, v70, 3, 0
	v_mul_f32_e32 v41, v48, v41
	s_waitcnt lgkmcnt(0)
	v_mul_f32_e32 v43, v57, v41
	v_fma_f32 v41, v58, s66, 0.5
	v_fma_f32 v41, v58, v41, 1.0
	ds_write_b64 v59, v[42:43] offset:36864
	v_mul_f32_e32 v41, v58, v41
	v_fma_f32 v42, v40, v40, -1.0
	v_cmp_lt_f32_e32 vcc, s79, v58
	s_movk_i32 s3, 0x1c80
	v_add3_u32 v57, v96, s3, v94
	v_cndmask_b32_e32 v41, v42, v41, vcc
	v_max_f32_e64 v41, -v41, 0
	v_sqrt_f32_e32 v41, v41
	ds_read_b32 v42, v57 offset:12288
	v_or_b32_e32 v58, 19, v60
	s_waitcnt vmcnt(0)
	v_mfma_f32_16x16x32_bf16 v[84:87], v[12:15], v[194:197], v[84:87]
	v_mul_f32_e32 v41, v68, v41
	v_add_u32_e32 v43, v77, v72
	s_waitcnt lgkmcnt(0)
	v_mul_f32_e32 v41, v42, v41
	v_mad_u32_u24 v42, v58, s46, v93
	v_lshl_add_u32 v42, v42, 3, 0
	ds_write_b64 v42, v[40:41] offset:36864
	ds_read_b32 v59, v74 offset:1984
	s_waitcnt vmcnt(0)
	v_mfma_f32_16x16x32_bf16 v[84:87], v[24:27], v[198:201], v[84:87]
	ds_read_b32 v68, v74 offset:2368
	ds_read_b32 v48, v75 offset:3520
	ds_read_b32 v77, v76 offset:12352
	v_mad_u32_u24 v92, v60, s46, v73
	v_mad_i64_i32 v[66:67], s[22:23], v43, s94, v[66:67]
	s_waitcnt lgkmcnt(3)
	v_add_f32_e32 v36, v36, v59
	v_mul_f32_e32 v36, 0xbfb8aa3b, v36
	v_exp_f32_e32 v36, v36
	v_add_f32_e32 v37, v37, v59
	v_mul_f32_e32 v37, 0xbfb8aa3b, v37
	v_exp_f32_e32 v37, v37
	v_add_f32_e32 v36, 1.0, v36
	v_rcp_f32_e32 v71, v36
	s_waitcnt lgkmcnt(2)
	v_add_f32_e32 v36, v84, v68
	v_mul_f32_e32 v36, 0xbfb8aa3b, v36
	v_exp_f32_e32 v36, v36
	v_add_f32_e32 v38, v38, v59
	v_mul_f32_e32 v38, 0xbfb8aa3b, v38
	v_exp_f32_e32 v38, v38
	v_add_f32_e32 v36, 1.0, v36
	v_rcp_f32_e32 v83, v36
	v_add_f32_e32 v36, 1.0, v37
	v_rcp_f32_e32 v70, v36
	v_add_f32_e32 v36, v85, v68
	v_mul_f32_e32 v36, 0xbfb8aa3b, v36
	v_exp_f32_e32 v93, v36
	v_pk_mul_f32 v[36:37], v[70:71], s[86:87] op_sel_hi:[1,0]
	v_mfma_f32_16x16x32_bf16 v[44:47], v[4:7], v[194:197], v[88:91]
	s_waitcnt lgkmcnt(1)
	v_pk_mul_f32 v[36:37], v[48:49], v[36:37] op_sel_hi:[0,1]
	v_mul_f32_e32 v70, 0x3fb8aa3b, v37
	v_exp_f32_e32 v70, v70
	v_pk_add_f32 v[84:85], v[36:37], v[36:37]
	v_mul_f32_e32 v36, 0x3fb8aa3b, v36
	v_fma_f32 v37, v85, s66, 0.5
	v_fma_f32 v37, v85, v37, 1.0
	v_mul_f32_e32 v37, v85, v37
	v_fma_f32 v71, v70, v70, -1.0
	v_cmp_lt_f32_e32 vcc, s79, v85
	v_exp_f32_e32 v36, v36
	v_lshl_add_u32 v85, v92, 3, 0
	v_cndmask_b32_e32 v37, v71, v37, vcc
	v_max_f32_e64 v37, -v37, 0
	v_sqrt_f32_e32 v37, v37
	v_add_f32_e32 v71, 1.0, v93
	v_rcp_f32_e32 v92, v71
	v_cmp_lt_f32_e32 vcc, s79, v84
	v_mul_f32_e32 v37, v83, v37
	s_waitcnt lgkmcnt(0)
	v_mul_f32_e32 v71, v77, v37
	v_fma_f32 v37, v84, s66, 0.5
	v_fma_f32 v37, v84, v37, 1.0
	ds_write_b64 v85, v[70:71] offset:36864
	v_mul_f32_e32 v37, v84, v37
	v_fma_f32 v70, v36, v36, -1.0
	v_cndmask_b32_e32 v37, v70, v37, vcc
	v_max_f32_e64 v37, -v37, 0
	v_sqrt_f32_e32 v37, v37
	ds_read_b32 v70, v62 offset:12352
	v_add_f32_e32 v71, v86, v68
	v_mul_f32_e32 v71, 0xbfb8aa3b, v71
	v_mul_f32_e32 v37, v92, v37
	v_exp_f32_e32 v71, v71
	s_waitcnt lgkmcnt(0)
	v_mul_f32_e32 v37, v70, v37
	v_mad_u32_u24 v70, v63, s46, v73
	v_lshl_add_u32 v70, v70, 3, 0
	ds_write_b64 v70, v[36:37] offset:36864
	v_add_f32_e32 v36, 1.0, v38
	v_add_f32_e32 v38, v39, v59
	v_mul_f32_e32 v38, 0xbfb8aa3b, v38
	v_exp_f32_e32 v38, v38
	v_rcp_f32_e32 v37, v36
	v_add_f32_e32 v36, 1.0, v71
	v_rcp_f32_e32 v39, v36
	v_add_f32_e32 v36, 1.0, v38
	v_rcp_f32_e32 v36, v36
	v_add_f32_e32 v38, v87, v68
	v_mul_f32_e32 v38, 0xbfb8aa3b, v38
	v_exp_f32_e32 v84, v38
	v_pk_mul_f32 v[36:37], v[36:37], s[86:87] op_sel_hi:[1,0]
	ds_read_b32 v77, v61 offset:12352
	v_pk_mul_f32 v[36:37], v[48:49], v[36:37] op_sel_hi:[0,1]
	v_mul_f32_e32 v38, 0x3fb8aa3b, v37
	v_exp_f32_e32 v38, v38
	v_pk_add_f32 v[70:71], v[36:37], v[36:37]
	v_mad_u32_u24 v83, v78, s46, v73
	v_fma_f32 v37, v71, s66, 0.5
	v_fma_f32 v37, v71, v37, 1.0
	v_mul_f32_e32 v37, v71, v37
	v_fma_f32 v85, v38, v38, -1.0
	v_cmp_lt_f32_e32 vcc, s79, v71
	v_mul_f32_e32 v36, 0x3fb8aa3b, v36
	v_lshl_add_u32 v71, v83, 3, 0
	v_cndmask_b32_e32 v37, v85, v37, vcc
	v_max_f32_e64 v37, -v37, 0
	v_sqrt_f32_e32 v37, v37
	v_add_f32_e32 v83, 1.0, v84
	v_exp_f32_e32 v84, v36
	s_cmp_lg_u32 s101, 0
	s_cbranch_scc1 .Llruw1_15
	global_load_dwordx4 v[202:205], v[66:67], off
.Llruw1_15:
	v_fma_f32 v36, v70, s66, 0.5
	v_mfma_f32_16x16x32_bf16 v[44:47], v[0:3], v[198:201], v[44:47]
	v_mul_f32_e32 v37, v39, v37
	v_fma_f32 v36, v70, v36, 1.0
	s_waitcnt lgkmcnt(0)
	v_mul_f32_e32 v39, v77, v37
	v_mul_f32_e32 v36, v70, v36
	v_fma_f32 v37, v84, v84, -1.0
	v_cmp_lt_f32_e32 vcc, s79, v70
	v_add_f32_e32 v32, v32, v59
	ds_write_b64 v71, v[38:39] offset:36864
	v_cndmask_b32_e32 v36, v37, v36, vcc
	v_max_f32_e64 v36, -v36, 0
	v_mul_f32_e32 v32, 0xbfb8aa3b, v32
	v_add_f32_e32 v44, v44, v68
	v_rcp_f32_e32 v83, v83
	v_sqrt_f32_e32 v70, v36
	ds_read_b32 v71, v80 offset:12352
	v_exp_f32_e32 v32, v32
	v_mul_f32_e32 v44, 0xbfb8aa3b, v44
	v_add_f32_e32 v33, v33, v59
	v_exp_f32_e32 v44, v44
	v_mul_f32_e32 v33, 0xbfb8aa3b, v33
	v_exp_f32_e32 v33, v33
	s_cmp_lg_u32 s101, 0
	s_cbranch_scc1 .Llruw1_16
	global_load_dwordx4 v[206:209], v[66:67], off offset:64
.Llruw1_16:
	s_cmp_lg_u32 s101, 0
	s_cbranch_scc1 .Llruw1_17
	global_load_dwordx4 v[210:213], v[66:67], off offset:128
.Llruw1_17:
	v_mul_f32_e32 v66, v83, v70
	v_add_f32_e32 v32, 1.0, v32
	s_waitcnt lgkmcnt(0)
	v_mul_f32_e32 v85, v71, v66
	v_mad_u32_u24 v66, v81, s46, v73
	v_rcp_f32_e32 v67, v32
	v_add_f32_e32 v32, 1.0, v44
	v_lshl_add_u32 v66, v66, 3, 0
	v_rcp_f32_e32 v70, v32
	v_add_f32_e32 v32, 1.0, v33
	ds_write_b64 v66, v[84:85] offset:36864
	v_rcp_f32_e32 v66, v32
	v_add_f32_e32 v32, v45, v68
	v_mul_f32_e32 v32, 0xbfb8aa3b, v32
	v_exp_f32_e32 v45, v32
	v_pk_mul_f32 v[32:33], v[66:67], s[86:87] op_sel_hi:[1,0]
	ds_read_b32 v71, v79 offset:12352
	v_pk_mul_f32 v[32:33], v[48:49], v[32:33] op_sel_hi:[0,1]
	v_mul_f32_e32 v44, 0x3fb8aa3b, v33
	v_exp_f32_e32 v44, v44
	v_pk_add_f32 v[66:67], v[32:33], v[32:33]
	v_mul_f32_e32 v32, 0x3fb8aa3b, v32
	v_fma_f32 v33, v67, s66, 0.5
	v_fma_f32 v33, v67, v33, 1.0
	v_mul_f32_e32 v33, v67, v33
	v_fma_f32 v83, v44, v44, -1.0
	v_cmp_lt_f32_e32 vcc, s79, v67
	v_exp_f32_e32 v32, v32
	v_mad_u32_u24 v77, v49, s46, v73
	v_cndmask_b32_e32 v33, v83, v33, vcc
	v_max_f32_e64 v33, -v33, 0
	v_sqrt_f32_e32 v33, v33
	v_add_f32_e32 v45, 1.0, v45
	v_lshl_add_u32 v67, v77, 3, 0
	v_rcp_f32_e32 v77, v45
	v_mul_f32_e32 v33, v70, v33
	s_waitcnt lgkmcnt(0)
	v_mul_f32_e32 v45, v71, v33
	v_fma_f32 v33, v66, s66, 0.5
	v_fma_f32 v33, v66, v33, 1.0
	ds_write_b64 v67, v[44:45] offset:36864
	v_mul_f32_e32 v33, v66, v33
	v_fma_f32 v44, v32, v32, -1.0
	v_cmp_lt_f32_e32 vcc, s79, v66
	v_add_f32_e32 v34, v34, v59
	v_mul_f32_e32 v34, 0xbfb8aa3b, v34
	v_cndmask_b32_e32 v33, v44, v33, vcc
	v_max_f32_e64 v33, -v33, 0
	v_sqrt_f32_e32 v33, v33
	ds_read_b32 v44, v82 offset:12352
	v_exp_f32_e32 v34, v34
	v_add_f32_e32 v45, v46, v68
	v_mul_f32_e32 v33, v77, v33
	v_mul_f32_e32 v45, 0xbfb8aa3b, v45
	s_waitcnt lgkmcnt(0)
	v_mul_f32_e32 v33, v44, v33
	v_mad_u32_u24 v44, v56, s46, v73
	v_lshl_add_u32 v44, v44, 3, 0
	ds_write_b64 v44, v[32:33] offset:36864
	v_add_f32_e32 v32, 1.0, v34
	v_add_f32_e32 v34, v35, v59
	v_exp_f32_e32 v45, v45
	v_mul_f32_e32 v34, 0xbfb8aa3b, v34
	v_exp_f32_e32 v34, v34
	v_rcp_f32_e32 v33, v32
	v_add_f32_e32 v32, 1.0, v45
	v_rcp_f32_e32 v35, v32
	v_add_f32_e32 v32, 1.0, v34
	v_rcp_f32_e32 v32, v32
	v_add_f32_e32 v34, v47, v68
	v_mul_f32_e32 v34, 0xbfb8aa3b, v34
	v_exp_f32_e32 v47, v34
	v_pk_mul_f32 v[32:33], v[32:33], s[86:87] op_sel_hi:[1,0]
	ds_read_b32 v46, v50 offset:12352
	v_pk_mul_f32 v[32:33], v[48:49], v[32:33] op_sel_hi:[0,1]
	v_mul_f32_e32 v34, 0x3fb8aa3b, v33
	v_exp_f32_e32 v34, v34
	v_pk_add_f32 v[44:45], v[32:33], v[32:33]
	v_mul_f32_e32 v32, 0x3fb8aa3b, v32
	v_fma_f32 v33, v45, s66, 0.5
	v_fma_f32 v33, v45, v33, 1.0
	v_mul_f32_e32 v33, v45, v33
	v_fma_f32 v48, v34, v34, -1.0
	v_cmp_lt_f32_e32 vcc, s79, v45
	v_mad_u32_u24 v59, v51, s46, v73
	v_lshl_add_u32 v45, v59, 3, 0
	v_cndmask_b32_e32 v33, v48, v33, vcc
	v_max_f32_e64 v33, -v33, 0
	v_sqrt_f32_e32 v33, v33
	v_cmp_lt_f32_e32 vcc, s79, v44
	v_add_f32_e32 v47, 1.0, v47
	v_rcp_f32_e32 v47, v47
	v_mul_f32_e32 v33, v35, v33
	s_waitcnt lgkmcnt(0)
	v_mul_f32_e32 v35, v46, v33
	v_exp_f32_e32 v46, v32
	v_fma_f32 v32, v44, s66, 0.5
	v_fma_f32 v32, v44, v32, 1.0
	v_mul_f32_e32 v32, v44, v32
	v_fma_f32 v33, v46, v46, -1.0
	v_cndmask_b32_e32 v32, v33, v32, vcc
	ds_write_b64 v45, v[34:35] offset:36864
	v_max_f32_e64 v32, -v32, 0
	v_sqrt_f32_e32 v44, v32
	ds_read_b32 v45, v57 offset:12352
	s_waitcnt vmcnt(0)
	v_mfma_f32_16x16x32_bf16 v[32:35], v[8:11], v[202:205], 0
	v_mul_f32_e32 v8, v47, v44
	s_waitcnt lgkmcnt(0)
	v_mul_f32_e32 v47, v45, v8
	v_mad_u32_u24 v8, v58, s46, v73
	v_lshl_add_u32 v8, v8, 3, 0
	v_mfma_f32_16x16x32_bf16 v[20:23], v[20:23], v[202:205], 0
	ds_write_b64 v8, v[46:47] offset:36864
	ds_read_b32 v9, v74 offset:2048
	s_waitcnt vmcnt(0)
	v_mfma_f32_16x16x32_bf16 v[10:13], v[12:15], v[206:209], v[20:23]
	s_nop 3
	ds_read_b32 v22, v74 offset:2432
	ds_read_b32 v8, v75 offset:3584
	ds_read_b32 v23, v76 offset:12416
	s_waitcnt lgkmcnt(3)
	v_add_f32_e32 v14, v28, v9
	v_mul_f32_e32 v14, 0xbfb8aa3b, v14
	v_exp_f32_e32 v14, v14
	s_waitcnt vmcnt(0)
	v_mfma_f32_16x16x32_bf16 v[10:13], v[24:27], v[210:213], v[10:13]
	v_or_b32_e32 v24, v72, v69
	v_mad_u32_u24 v26, v60, s46, v24
	v_add_f32_e32 v14, 1.0, v14
	v_rcp_f32_e32 v15, v14
	v_add_f32_e32 v14, v29, v9
	s_waitcnt lgkmcnt(2)
	s_nop 1
	v_add_f32_e32 v10, v10, v22
	v_mul_f32_e32 v10, 0xbfb8aa3b, v10
	v_exp_f32_e32 v10, v10
	v_mul_f32_e32 v14, 0xbfb8aa3b, v14
	v_exp_f32_e32 v14, v14
	v_add_f32_e32 v12, v12, v22
	v_add_f32_e32 v10, 1.0, v10
	v_rcp_f32_e32 v25, v10
	v_add_f32_e32 v10, 1.0, v14
	v_rcp_f32_e32 v14, v10
	v_add_f32_e32 v10, v11, v22
	v_mul_f32_e32 v10, 0xbfb8aa3b, v10
	v_exp_f32_e32 v27, v10
	v_pk_mul_f32 v[10:11], v[14:15], s[86:87] op_sel_hi:[1,0]
	v_mul_f32_e32 v12, 0xbfb8aa3b, v12
	s_waitcnt lgkmcnt(1)
	v_pk_mul_f32 v[10:11], v[8:9], v[10:11] op_sel_hi:[0,1]
	v_mul_f32_e32 v14, 0x3fb8aa3b, v11
	v_exp_f32_e32 v14, v14
	v_pk_add_f32 v[20:21], v[10:11], v[10:11]
	v_mul_f32_e32 v10, 0x3fb8aa3b, v10
	v_fma_f32 v11, v21, s66, 0.5
	v_fma_f32 v11, v21, v11, 1.0
	v_mul_f32_e32 v11, v21, v11
	v_fma_f32 v15, v14, v14, -1.0
	v_cmp_lt_f32_e32 vcc, s79, v21
	v_exp_f32_e32 v10, v10
	v_lshl_add_u32 v21, v26, 3, 0
	v_cndmask_b32_e32 v11, v15, v11, vcc
	v_max_f32_e64 v11, -v11, 0
	v_sqrt_f32_e32 v11, v11
	v_add_f32_e32 v15, 1.0, v27
	v_rcp_f32_e32 v26, v15
	v_cmp_lt_f32_e32 vcc, s79, v20
	v_mul_f32_e32 v11, v25, v11
	s_waitcnt lgkmcnt(0)
	v_mul_f32_e32 v15, v23, v11
	v_fma_f32 v11, v20, s66, 0.5
	v_fma_f32 v11, v20, v11, 1.0
	ds_write_b64 v21, v[14:15] offset:36864
	v_mul_f32_e32 v11, v20, v11
	v_fma_f32 v14, v10, v10, -1.0
	v_cndmask_b32_e32 v11, v14, v11, vcc
	v_max_f32_e64 v11, -v11, 0
	v_sqrt_f32_e32 v11, v11
	ds_read_b32 v14, v62 offset:12416
	v_add_f32_e32 v15, v30, v9
	v_mul_f32_e32 v15, 0xbfb8aa3b, v15
	v_exp_f32_e32 v15, v15
	v_mul_f32_e32 v11, v26, v11
	v_exp_f32_e32 v12, v12
	s_waitcnt lgkmcnt(0)
	v_mul_f32_e32 v11, v14, v11
	v_mad_u32_u24 v14, v63, s46, v24
	v_lshl_add_u32 v14, v14, 3, 0
	ds_write_b64 v14, v[10:11] offset:36864
	v_add_f32_e32 v10, 1.0, v15
	v_rcp_f32_e32 v11, v10
	v_add_f32_e32 v10, 1.0, v12
	v_add_f32_e32 v12, v31, v9
	v_mul_f32_e32 v12, 0xbfb8aa3b, v12
	v_exp_f32_e32 v12, v12
	v_rcp_f32_e32 v20, v10
	ds_read_b32 v21, v61 offset:12416
	v_mad_u32_u24 v23, v78, s46, v24
	v_add_f32_e32 v10, 1.0, v12
	v_rcp_f32_e32 v10, v10
	v_add_f32_e32 v12, v13, v22
	v_mul_f32_e32 v12, 0xbfb8aa3b, v12
	v_exp_f32_e32 v13, v12
	v_pk_mul_f32 v[10:11], v[10:11], s[86:87] op_sel_hi:[1,0]
	v_mfma_f32_16x16x32_bf16 v[4:7], v[4:7], v[206:209], v[32:35]
	v_mul_f32_e64 v10, v8, v10
	v_mul_f32_e64 v11, v8, v11
	v_mul_f32_e32 v12, 0x3fb8aa3b, v11
	v_exp_f32_e32 v12, v12
	v_pk_add_f32 v[14:15], v[10:11], v[10:11]
	v_mul_f32_e32 v10, 0x3fb8aa3b, v10
	v_fma_f32 v11, v15, s66, 0.5
	v_fma_f32 v11, v15, v11, 1.0
	v_mul_f32_e32 v11, v15, v11
	v_fma_f32 v25, v12, v12, -1.0
	v_cmp_lt_f32_e32 vcc, s79, v15
	v_exp_f32_e32 v10, v10
	v_add_f32_e32 v13, 1.0, v13
	v_cndmask_b32_e32 v11, v25, v11, vcc
	v_max_f32_e64 v11, -v11, 0
	v_sqrt_f32_e32 v11, v11
	v_lshl_add_u32 v15, v23, 3, 0
	v_rcp_f32_e32 v23, v13
	v_cmp_lt_f32_e32 vcc, s79, v14
	v_mul_f32_e32 v11, v20, v11
	s_waitcnt lgkmcnt(0)
	v_mul_f32_e32 v13, v21, v11
	v_fma_f32 v11, v14, s66, 0.5
	v_fma_f32 v11, v14, v11, 1.0
	ds_write_b64 v15, v[12:13] offset:36864
	v_mul_f32_e32 v11, v14, v11
	v_fma_f32 v12, v10, v10, -1.0
	v_cndmask_b32_e32 v11, v12, v11, vcc
	v_max_f32_e64 v11, -v11, 0
	v_sqrt_f32_e32 v11, v11
	ds_read_b32 v12, v80 offset:12416
	v_mfma_f32_16x16x32_bf16 v[0:3], v[0:3], v[210:213], v[4:7]
	s_nop 2
	v_add_f32_e32 v5, v16, v9
	v_mul_f32_e32 v5, 0xbfb8aa3b, v5
	v_exp_f32_e32 v5, v5
	v_mul_f32_e32 v4, v23, v11
	s_waitcnt lgkmcnt(0)
	v_mul_f32_e32 v11, v12, v4
	v_mad_u32_u24 v4, v81, s46, v24
	v_lshl_add_u32 v4, v4, 3, 0
	v_add_f32_e32 v0, v0, v22
	ds_write_b64 v4, v[10:11] offset:36864
	v_add_f32_e32 v4, 1.0, v5
	v_mul_f32_e32 v0, 0xbfb8aa3b, v0
	v_rcp_f32_e32 v5, v4
	v_add_f32_e32 v4, v17, v9
	v_exp_f32_e32 v0, v0
	v_mul_f32_e32 v4, 0xbfb8aa3b, v4
	v_exp_f32_e32 v4, v4
	ds_read_b32 v11, v79 offset:12416
	v_add_f32_e32 v0, 1.0, v0
	v_rcp_f32_e32 v10, v0
	v_add_f32_e32 v0, 1.0, v4
	v_rcp_f32_e32 v4, v0
	v_add_f32_e32 v0, v1, v22
	v_mul_f32_e32 v0, 0xbfb8aa3b, v0
	v_exp_f32_e32 v13, v0
	v_pk_mul_f32 v[0:1], v[4:5], s[86:87] op_sel_hi:[1,0]
	v_mad_u32_u24 v12, v49, s46, v24
	v_pk_mul_f32 v[0:1], v[8:9], v[0:1] op_sel_hi:[0,1]
	v_mul_f32_e32 v4, 0x3fb8aa3b, v1
	v_exp_f32_e32 v4, v4
	v_pk_add_f32 v[6:7], v[0:1], v[0:1]
	v_mul_f32_e32 v0, 0x3fb8aa3b, v0
	v_fma_f32 v1, v7, s66, 0.5
	v_fma_f32 v1, v7, v1, 1.0
	v_mul_f32_e32 v1, v7, v1
	v_fma_f32 v5, v4, v4, -1.0
	v_cmp_lt_f32_e32 vcc, s79, v7
	v_exp_f32_e32 v0, v0
	v_lshl_add_u32 v7, v12, 3, 0
	v_cndmask_b32_e32 v1, v5, v1, vcc
	v_max_f32_e64 v1, -v1, 0
	v_sqrt_f32_e32 v1, v1
	v_add_f32_e32 v5, 1.0, v13
	v_rcp_f32_e32 v12, v5
	v_cmp_lt_f32_e32 vcc, s79, v6
	v_mul_f32_e32 v1, v10, v1
	s_waitcnt lgkmcnt(0)
	v_mul_f32_e32 v5, v11, v1
	v_fma_f32 v1, v6, s66, 0.5
	v_fma_f32 v1, v6, v1, 1.0
	ds_write_b64 v7, v[4:5] offset:36864
	v_mul_f32_e32 v1, v6, v1
	v_fma_f32 v4, v0, v0, -1.0
	v_cndmask_b32_e32 v1, v4, v1, vcc
	v_max_f32_e64 v1, -v1, 0
	v_sqrt_f32_e32 v1, v1
	ds_read_b32 v4, v82 offset:12416
	v_add_f32_e32 v5, v18, v9
	v_mul_f32_e32 v5, 0xbfb8aa3b, v5
	v_add_f32_e32 v2, v2, v22
	v_exp_f32_e32 v5, v5
	v_mul_f32_e32 v2, 0xbfb8aa3b, v2
	v_mul_f32_e32 v1, v12, v1
	v_exp_f32_e32 v2, v2
	s_waitcnt lgkmcnt(0)
	v_mul_f32_e32 v1, v4, v1
	v_mad_u32_u24 v4, v56, s46, v24
	v_lshl_add_u32 v4, v4, 3, 0
	ds_write_b64 v4, v[0:1] offset:36864
	v_add_f32_e32 v0, 1.0, v5
	v_rcp_f32_e32 v1, v0
	v_add_f32_e32 v0, 1.0, v2
	v_add_f32_e32 v2, v19, v9
	v_mul_f32_e32 v2, 0xbfb8aa3b, v2
	v_exp_f32_e32 v2, v2
	v_rcp_f32_e32 v6, v0
	v_mad_u32_u24 v9, v51, s46, v24
	ds_read_b32 v7, v50 offset:12416
	v_add_f32_e32 v0, 1.0, v2
	v_rcp_f32_e32 v0, v0
	v_add_f32_e32 v2, v3, v22
	v_mul_f32_e32 v2, 0xbfb8aa3b, v2
	v_exp_f32_e32 v3, v2
	v_pk_mul_f32 v[0:1], v[0:1], s[86:87] op_sel_hi:[1,0]
	v_add_f32_e32 v3, 1.0, v3
	v_pk_mul_f32 v[0:1], v[8:9], v[0:1] op_sel_hi:[0,1]
	v_mul_f32_e32 v2, 0x3fb8aa3b, v1
	v_exp_f32_e32 v2, v2
	v_pk_add_f32 v[4:5], v[0:1], v[0:1]
	v_mul_f32_e32 v0, 0x3fb8aa3b, v0
	v_fma_f32 v1, v5, s66, 0.5
	v_fma_f32 v1, v5, v1, 1.0
	v_mul_f32_e32 v1, v5, v1
	v_fma_f32 v8, v2, v2, -1.0
	v_cmp_lt_f32_e32 vcc, s79, v5
	v_exp_f32_e32 v0, v0
	v_lshl_add_u32 v5, v9, 3, 0
	v_cndmask_b32_e32 v1, v8, v1, vcc
	v_max_f32_e64 v1, -v1, 0
	v_sqrt_f32_e32 v1, v1
	v_rcp_f32_e32 v8, v3
	v_cmp_lt_f32_e32 vcc, s79, v4
	v_mul_f32_e32 v1, v6, v1
	s_waitcnt lgkmcnt(0)
	v_mul_f32_e32 v3, v7, v1
	v_fma_f32 v1, v4, s66, 0.5
	v_fma_f32 v1, v4, v1, 1.0
	ds_write_b64 v5, v[2:3] offset:36864
	v_mul_f32_e32 v1, v4, v1
	v_fma_f32 v2, v0, v0, -1.0
	v_cndmask_b32_e32 v1, v2, v1, vcc
	v_max_f32_e64 v1, -v1, 0
	v_sqrt_f32_e32 v1, v1
	ds_read_b32 v2, v57 offset:12416
	v_cmp_gt_i32_e32 vcc, s94, v65
	v_mul_f32_e32 v1, v8, v1
	s_waitcnt lgkmcnt(0)
	v_mul_f32_e32 v1, v2, v1
	v_mad_u32_u24 v2, v58, s46, v24
	v_lshl_add_u32 v2, v2, 3, 0
	ds_write_b64 v2, v[0:1] offset:36864
	s_waitcnt lgkmcnt(0)
	s_mov_b32 s101, 1
	s_barrier
	s_and_saveexec_b64 s[22:23], vcc
	s_cbranch_execz .LBB0_1249
	v_mul_hi_i32 v0, v65, s81
	v_lshrrev_b32_e32 v1, 31, v0
	v_ashrrev_i32_e32 v0, 4, v0
	v_add_u32_e32 v1, v0, v1
	v_mul_lo_u32 v0, v1, s46
	s_lshl_b32 s30, s37, 9
	v_sub_u32_e32 v0, v65, v0
	s_mulk_i32 s39, 0x60
	v_lshl_add_u32 v3, v1, 8, s30
	v_add_u32_e32 v2, s39, v0
	v_or_b32_e32 v6, s40, v3
	v_mov_b64_e32 v[4:5], s[20:21]
	v_ashrrev_i32_e32 v3, 31, v2
	v_mad_i64_i32 v[4:5], s[20:21], v6, s69, v[4:5]
	v_lshl_add_u64 v[2:3], v[2:3], 2, v[4:5]
	s_mov_b32 s20, 0x900000
	v_add_co_u32_e32 v2, vcc, s20, v2
	s_movk_i32 s3, 0x1800
	s_nop 0
	v_addc_co_u32_e32 v3, vcc, 0, v3, vcc
	global_load_dword v7, v[2:3], off
	v_mad_u64_u32 v[0:1], s[20:21], v1, s3, v[0:1]
	v_lshl_add_u32 v6, v0, 3, 0
	v_add_u32_e32 v0, 0x5f, v65
	s_movk_i32 s3, 0xbf
	v_cmp_gt_u32_e32 vcc, s3, v0
	v_mov_b32_e32 v26, 0xbd00
	v_mov_b32_e32 v27, 0xba00
	v_cndmask_b32_e64 v0, v26, 0, vcc
	v_add_u32_e32 v18, v6, v0
	v_cndmask_b32_e32 v2, v27, v233, vcc
	v_mov_b32_e32 v28, 0xb700
	v_mov_b32_e32 v29, 0x600
	ds_read_b64 v[0:1], v18 offset:36864
	v_add_u32_e32 v19, v6, v2
	v_cndmask_b32_e32 v4, v28, v29, vcc
	v_mov_b32_e32 v30, 0xb400
	v_mov_b32_e32 v31, 0x900
	ds_read_b64 v[2:3], v19 offset:36864
	v_add_u32_e32 v20, v6, v4
	v_cndmask_b32_e32 v8, v30, v31, vcc
	v_mov_b32_e32 v32, 0xb100
	v_mov_b32_e32 v33, 0xc00
	ds_read_b64 v[4:5], v20 offset:36864
	v_add_u32_e32 v21, v6, v8
	v_cndmask_b32_e32 v10, v32, v33, vcc
	v_mov_b32_e32 v34, 0xae00
	v_mov_b32_e32 v35, 0xf00
	ds_read_b64 v[8:9], v21 offset:36864
	v_add_u32_e32 v22, v6, v10
	v_cndmask_b32_e32 v12, v34, v35, vcc
	v_mov_b32_e32 v36, 0xab00
	v_mov_b32_e32 v37, 0x1200
	ds_read_b64 v[10:11], v22 offset:36864
	v_add_u32_e32 v23, v6, v12
	v_cndmask_b32_e32 v14, v36, v37, vcc
	v_mov_b32_e32 v38, 0xa800
	v_mov_b32_e32 v39, 0x1500
	ds_read_b64 v[12:13], v23 offset:36864
	v_add_u32_e32 v24, v6, v14
	v_cndmask_b32_e32 v16, v38, v39, vcc
	ds_read_b64 v[14:15], v24 offset:36864
	v_add_u32_e32 v25, v6, v16
	ds_read_b64 v[16:17], v25 offset:36864
	v_mov_b32_e32 v40, 0xa500
	v_mov_b32_e32 v41, 0x1800
	v_mov_b32_e32 v42, 0xa200
	v_mov_b32_e32 v43, 0x1b00
	v_mov_b32_e32 v44, 0x9f00
	v_mov_b32_e32 v45, 0x1e00
	v_mov_b32_e32 v46, 0x9c00
	v_mov_b32_e32 v47, 0x2100
	v_mov_b32_e32 v48, 0x9900
	v_mov_b32_e32 v49, 0x2400
	v_mov_b32_e32 v50, 0x9600
	v_mov_b32_e32 v51, 0x2700
	v_mov_b32_e32 v52, 0x9300
	v_mov_b32_e32 v53, 0x2a00
	v_mov_b32_e32 v54, 0x9000
	v_mov_b32_e32 v55, 0x2d00
	v_mov_b32_e32 v56, 0x8d00
	v_mov_b32_e32 v57, 0x3000
	v_mov_b32_e32 v58, 0x8a00
	v_mov_b32_e32 v59, 0x3300
	v_mov_b32_e32 v60, 0x8700
	v_mov_b32_e32 v61, 0x3600
	v_mov_b32_e32 v62, 0x8400
	v_mov_b32_e32 v63, 0x3900
	v_mov_b32_e32 v66, 0x8100
	v_mov_b32_e32 v67, 0x3c00
	v_mov_b32_e32 v68, 0x7e00
	v_mov_b32_e32 v69, 0x3f00
	v_mov_b32_e32 v70, 0x7b00
	v_mov_b32_e32 v71, 0x4200
	v_mov_b32_e32 v72, 0x7800
	v_mov_b32_e32 v73, 0x4500
	v_mov_b32_e32 v74, 0x7500
	v_mov_b32_e32 v75, 0x4800
	v_mov_b32_e32 v76, 0x7200
	s_waitcnt vmcnt(0) lgkmcnt(7)
	v_fmac_f32_e32 v1, v7, v0
	s_waitcnt lgkmcnt(6)
	v_fmac_f32_e32 v3, v2, v1
	s_waitcnt lgkmcnt(5)
	v_fmac_f32_e32 v5, v4, v3
	s_waitcnt lgkmcnt(4)
	v_fmac_f32_e32 v9, v8, v5
	s_waitcnt lgkmcnt(3)
	v_fmac_f32_e32 v11, v10, v9
	s_waitcnt lgkmcnt(2)
	v_fmac_f32_e32 v13, v12, v11
	s_waitcnt lgkmcnt(1)
	v_fmac_f32_e32 v15, v14, v13
	v_cndmask_b32_e32 v0, v40, v41, vcc
	s_waitcnt lgkmcnt(0)
	v_fmac_f32_e32 v17, v16, v15
	ds_write_b32 v18, v1 offset:36868
	ds_write_b32 v19, v3 offset:36868
	ds_write_b32 v20, v5 offset:36868
	ds_write_b32 v21, v9 offset:36868
	ds_write_b32 v22, v11 offset:36868
	ds_write_b32 v23, v13 offset:36868
	ds_write_b32 v24, v15 offset:36868
	ds_write_b32 v25, v17 offset:36868
	v_add_u32_e32 v7, v6, v0
	v_cndmask_b32_e32 v0, v42, v43, vcc
	ds_read_b64 v[2:3], v7 offset:36864
	v_add_u32_e32 v16, v6, v0
	v_cndmask_b32_e32 v0, v44, v45, vcc
	ds_read_b64 v[4:5], v16 offset:36864
	v_add_u32_e32 v20, v6, v0
	v_cndmask_b32_e32 v0, v46, v47, vcc
	ds_read_b64 v[8:9], v20 offset:36864
	v_add_u32_e32 v21, v6, v0
	v_cndmask_b32_e32 v0, v48, v49, vcc
	ds_read_b64 v[10:11], v21 offset:36864
	v_add_u32_e32 v22, v6, v0
	v_cndmask_b32_e32 v0, v50, v51, vcc
	ds_read_b64 v[12:13], v22 offset:36864
	v_add_u32_e32 v23, v6, v0
	v_cndmask_b32_e32 v0, v52, v53, vcc
	ds_read_b64 v[14:15], v23 offset:36864
	v_add_u32_e32 v24, v6, v0
	v_cndmask_b32_e32 v0, v54, v55, vcc
	s_waitcnt lgkmcnt(5)
	v_fmac_f32_e32 v3, v17, v2
	ds_read_b64 v[18:19], v24 offset:36864
	v_add_u32_e32 v25, v6, v0
	s_waitcnt lgkmcnt(5)
	v_fmac_f32_e32 v5, v4, v3
	ds_read_b64 v[0:1], v25 offset:36864
	s_waitcnt lgkmcnt(5)
	v_fmac_f32_e32 v9, v8, v5
	s_waitcnt lgkmcnt(4)
	v_fmac_f32_e32 v11, v10, v9
	s_waitcnt lgkmcnt(3)
	v_fmac_f32_e32 v13, v12, v11
	s_waitcnt lgkmcnt(2)
	v_fmac_f32_e32 v15, v14, v13
	s_waitcnt lgkmcnt(1)
	v_fmac_f32_e32 v19, v18, v15
	s_waitcnt lgkmcnt(0)
	v_fmac_f32_e32 v1, v0, v19
	v_cndmask_b32_e32 v0, v56, v57, vcc
	ds_write_b32 v7, v3 offset:36868
	ds_write_b32 v16, v5 offset:36868
	ds_write_b32 v20, v9 offset:36868
	ds_write_b32 v21, v11 offset:36868
	ds_write_b32 v22, v13 offset:36868
	ds_write_b32 v23, v15 offset:36868
	ds_write_b32 v24, v19 offset:36868
	ds_write_b32 v25, v1 offset:36868
	v_add_u32_e32 v0, v6, v0
	v_cndmask_b32_e32 v4, v58, v59, vcc
	ds_read_b64 v[2:3], v0 offset:36864
	v_add_u32_e32 v7, v6, v4
	v_cndmask_b32_e32 v8, v60, v61, vcc
	ds_read_b64 v[4:5], v7 offset:36864
	v_add_u32_e32 v20, v6, v8
	v_cndmask_b32_e32 v10, v62, v63, vcc
	ds_read_b64 v[8:9], v20 offset:36864
	v_add_u32_e32 v21, v6, v10
	v_cndmask_b32_e32 v12, v66, v67, vcc
	ds_read_b64 v[10:11], v21 offset:36864
	v_add_u32_e32 v22, v6, v12
	v_cndmask_b32_e32 v14, v68, v69, vcc
	ds_read_b64 v[12:13], v22 offset:36864
	v_add_u32_e32 v23, v6, v14
	v_cndmask_b32_e32 v16, v70, v71, vcc
	ds_read_b64 v[14:15], v23 offset:36864
	v_add_u32_e32 v24, v6, v16
	v_cndmask_b32_e32 v18, v72, v73, vcc
	s_waitcnt lgkmcnt(5)
	v_fmac_f32_e32 v3, v1, v2
	ds_read_b64 v[16:17], v24 offset:36864
	v_add_u32_e32 v25, v6, v18
	s_waitcnt lgkmcnt(5)
	v_fmac_f32_e32 v5, v4, v3
	ds_read_b64 v[18:19], v25 offset:36864
	s_waitcnt lgkmcnt(5)
	v_fmac_f32_e32 v9, v8, v5
	s_waitcnt lgkmcnt(4)
	v_fmac_f32_e32 v11, v10, v9
	s_waitcnt lgkmcnt(3)
	v_fmac_f32_e32 v13, v12, v11
	s_waitcnt lgkmcnt(2)
	v_fmac_f32_e32 v15, v14, v13
	s_waitcnt lgkmcnt(1)
	v_fmac_f32_e32 v17, v16, v15
	s_waitcnt lgkmcnt(0)
	v_fmac_f32_e32 v19, v18, v17
	ds_write_b32 v0, v3 offset:36868
	ds_write_b32 v7, v5 offset:36868
	ds_write_b32 v20, v9 offset:36868
	ds_write_b32 v21, v11 offset:36868
	ds_write_b32 v22, v13 offset:36868
	ds_write_b32 v23, v15 offset:36868
	ds_write_b32 v24, v17 offset:36868
	ds_write_b32 v25, v19 offset:36868
	v_cndmask_b32_e32 v0, v74, v75, vcc
	v_mov_b32_e32 v77, 0x4b00
	v_add_u32_e32 v7, v6, v0
	v_cndmask_b32_e32 v2, v76, v77, vcc
	v_mov_b32_e32 v78, 0x6f00
	v_mov_b32_e32 v79, 0x4e00
	ds_read_b64 v[0:1], v7 offset:36864
	v_add_u32_e32 v18, v6, v2
	v_cndmask_b32_e32 v4, v78, v79, vcc
	v_mov_b32_e32 v80, 0x6c00
	ds_read_b64 v[2:3], v18 offset:36864
	v_add_u32_e32 v20, v6, v4
	v_cndmask_b32_e32 v8, v80, v254, vcc
	v_mov_b32_e32 v81, 0x6900
	ds_read_b64 v[4:5], v20 offset:36864
	v_add_u32_e32 v21, v6, v8
	v_cndmask_b32_e32 v10, v81, v225, vcc
	v_mov_b32_e32 v82, 0x6600
	ds_read_b64 v[8:9], v21 offset:36864
	v_add_u32_e32 v22, v6, v10
	v_cndmask_b32_e32 v12, v82, v228, vcc
	ds_read_b64 v[10:11], v22 offset:36864
	v_add_u32_e32 v23, v6, v12
	v_cndmask_b32_e32 v14, v242, v243, vcc
	ds_read_b64 v[12:13], v23 offset:36864
	v_add_u32_e32 v24, v6, v14
	v_cndmask_b32_e32 v16, v244, v246, vcc
	s_waitcnt lgkmcnt(5)
	v_fmac_f32_e32 v1, v19, v0
	ds_read_b64 v[14:15], v24 offset:36864
	v_add_u32_e32 v25, v6, v16
	s_waitcnt lgkmcnt(5)
	v_fmac_f32_e32 v3, v2, v1
	ds_read_b64 v[16:17], v25 offset:36864
	s_waitcnt lgkmcnt(5)
	v_fmac_f32_e32 v5, v4, v3
	s_waitcnt lgkmcnt(4)
	v_fmac_f32_e32 v9, v8, v5
	s_waitcnt lgkmcnt(3)
	v_fmac_f32_e32 v11, v10, v9
	s_waitcnt lgkmcnt(2)
	v_fmac_f32_e32 v13, v12, v11
	s_waitcnt lgkmcnt(1)
	v_fmac_f32_e32 v15, v14, v13
	v_cndmask_b32_e32 v0, v246, v244, vcc
	s_waitcnt lgkmcnt(0)
	v_fmac_f32_e32 v17, v16, v15
	ds_write_b32 v7, v1 offset:36868
	ds_write_b32 v18, v3 offset:36868
	ds_write_b32 v20, v5 offset:36868
	ds_write_b32 v21, v9 offset:36868
	ds_write_b32 v22, v11 offset:36868
	ds_write_b32 v23, v13 offset:36868
	ds_write_b32 v24, v15 offset:36868
	ds_write_b32 v25, v17 offset:36868
	v_add_u32_e32 v7, v6, v0
	v_cndmask_b32_e32 v2, v243, v242, vcc
	ds_read_b64 v[0:1], v7 offset:36864
	v_add_u32_e32 v16, v6, v2
	v_cndmask_b32_e32 v4, v228, v82, vcc
	ds_read_b64 v[2:3], v16 offset:36864
	v_add_u32_e32 v20, v6, v4
	v_cndmask_b32_e32 v8, v225, v81, vcc
	ds_read_b64 v[4:5], v20 offset:36864
	v_add_u32_e32 v21, v6, v8
	v_cndmask_b32_e32 v10, v254, v80, vcc
	ds_read_b64 v[8:9], v21 offset:36864
	v_add_u32_e32 v22, v6, v10
	v_cndmask_b32_e32 v12, v79, v78, vcc
	ds_read_b64 v[10:11], v22 offset:36864
	v_add_u32_e32 v23, v6, v12
	v_cndmask_b32_e32 v14, v77, v76, vcc
	ds_read_b64 v[12:13], v23 offset:36864
	v_add_u32_e32 v24, v6, v14
	v_cndmask_b32_e32 v18, v75, v74, vcc
	s_waitcnt lgkmcnt(5)
	v_fmac_f32_e32 v1, v17, v0
	ds_read_b64 v[14:15], v24 offset:36864
	v_add_u32_e32 v25, v6, v18
	s_waitcnt lgkmcnt(5)
	v_fmac_f32_e32 v3, v2, v1
	ds_read_b64 v[18:19], v25 offset:36864
	s_waitcnt lgkmcnt(5)
	v_fmac_f32_e32 v5, v4, v3
	s_waitcnt lgkmcnt(4)
	v_fmac_f32_e32 v9, v8, v5
	s_waitcnt lgkmcnt(3)
	v_fmac_f32_e32 v11, v10, v9
	s_waitcnt lgkmcnt(2)
	v_fmac_f32_e32 v13, v12, v11
	s_waitcnt lgkmcnt(1)
	v_fmac_f32_e32 v15, v14, v13
	v_cndmask_b32_e32 v0, v73, v72, vcc
	s_waitcnt lgkmcnt(0)
	v_fmac_f32_e32 v19, v18, v15
	ds_write_b32 v7, v1 offset:36868
	ds_write_b32 v16, v3 offset:36868
	ds_write_b32 v20, v5 offset:36868
	ds_write_b32 v21, v9 offset:36868
	ds_write_b32 v22, v11 offset:36868
	ds_write_b32 v23, v13 offset:36868
	ds_write_b32 v24, v15 offset:36868
	ds_write_b32 v25, v19 offset:36868
	v_add_u32_e32 v7, v6, v0
	v_cndmask_b32_e32 v2, v71, v70, vcc
	ds_read_b64 v[0:1], v7 offset:36864
	v_add_u32_e32 v18, v6, v2
	v_cndmask_b32_e32 v4, v69, v68, vcc
	ds_read_b64 v[2:3], v18 offset:36864
	v_add_u32_e32 v20, v6, v4
	v_cndmask_b32_e32 v8, v67, v66, vcc
	ds_read_b64 v[4:5], v20 offset:36864
	v_add_u32_e32 v21, v6, v8
	v_cndmask_b32_e32 v10, v63, v62, vcc
	ds_read_b64 v[8:9], v21 offset:36864
	v_add_u32_e32 v22, v6, v10
	v_cndmask_b32_e32 v12, v61, v60, vcc
	ds_read_b64 v[10:11], v22 offset:36864
	v_add_u32_e32 v23, v6, v12
	v_cndmask_b32_e32 v14, v59, v58, vcc
	ds_read_b64 v[12:13], v23 offset:36864
	v_add_u32_e32 v24, v6, v14
	v_cndmask_b32_e32 v16, v57, v56, vcc
	s_waitcnt lgkmcnt(5)
	v_fmac_f32_e32 v1, v19, v0
	ds_read_b64 v[14:15], v24 offset:36864
	v_add_u32_e32 v25, v6, v16
	s_waitcnt lgkmcnt(5)
	v_fmac_f32_e32 v3, v2, v1
	ds_read_b64 v[16:17], v25 offset:36864
	s_waitcnt lgkmcnt(5)
	v_fmac_f32_e32 v5, v4, v3
	s_waitcnt lgkmcnt(4)
	v_fmac_f32_e32 v9, v8, v5
	s_waitcnt lgkmcnt(3)
	v_fmac_f32_e32 v11, v10, v9
	s_waitcnt lgkmcnt(2)
	v_fmac_f32_e32 v13, v12, v11
	s_waitcnt lgkmcnt(1)
	v_fmac_f32_e32 v15, v14, v13
	v_cndmask_b32_e32 v0, v55, v54, vcc
	s_waitcnt lgkmcnt(0)
	v_fmac_f32_e32 v17, v16, v15
	ds_write_b32 v7, v1 offset:36868
	ds_write_b32 v18, v3 offset:36868
	ds_write_b32 v20, v5 offset:36868
	ds_write_b32 v21, v9 offset:36868
	ds_write_b32 v22, v11 offset:36868
	ds_write_b32 v23, v13 offset:36868
	ds_write_b32 v24, v15 offset:36868
	ds_write_b32 v25, v17 offset:36868
	v_add_u32_e32 v7, v6, v0
	v_cndmask_b32_e32 v2, v53, v52, vcc
	ds_read_b64 v[0:1], v7 offset:36864
	v_add_u32_e32 v16, v6, v2
	v_cndmask_b32_e32 v4, v51, v50, vcc
	ds_read_b64 v[2:3], v16 offset:36864
	v_add_u32_e32 v20, v6, v4
	v_cndmask_b32_e32 v8, v49, v48, vcc
	ds_read_b64 v[4:5], v20 offset:36864
	v_add_u32_e32 v21, v6, v8
	v_cndmask_b32_e32 v10, v47, v46, vcc
	ds_read_b64 v[8:9], v21 offset:36864
	v_add_u32_e32 v22, v6, v10
	v_cndmask_b32_e32 v12, v45, v44, vcc
	ds_read_b64 v[10:11], v22 offset:36864
	v_add_u32_e32 v23, v6, v12
	v_cndmask_b32_e32 v14, v43, v42, vcc
	ds_read_b64 v[12:13], v23 offset:36864
	v_add_u32_e32 v24, v6, v14
	v_cndmask_b32_e32 v18, v41, v40, vcc
	s_waitcnt lgkmcnt(5)
	v_fmac_f32_e32 v1, v17, v0
	ds_read_b64 v[14:15], v24 offset:36864
	v_add_u32_e32 v25, v6, v18
	s_waitcnt lgkmcnt(5)
	v_fmac_f32_e32 v3, v2, v1
	ds_read_b64 v[18:19], v25 offset:36864
	s_waitcnt lgkmcnt(5)
	v_fmac_f32_e32 v5, v4, v3
	s_waitcnt lgkmcnt(4)
	v_fmac_f32_e32 v9, v8, v5
	s_waitcnt lgkmcnt(3)
	v_fmac_f32_e32 v11, v10, v9
	s_waitcnt lgkmcnt(2)
	v_fmac_f32_e32 v13, v12, v11
	s_waitcnt lgkmcnt(1)
	v_fmac_f32_e32 v15, v14, v13
	v_cndmask_b32_e32 v0, v39, v38, vcc
	s_waitcnt lgkmcnt(0)
	v_fmac_f32_e32 v19, v18, v15
	ds_write_b32 v7, v1 offset:36868
	ds_write_b32 v16, v3 offset:36868
	ds_write_b32 v20, v5 offset:36868
	ds_write_b32 v21, v9 offset:36868
	ds_write_b32 v22, v11 offset:36868
	ds_write_b32 v23, v13 offset:36868
	ds_write_b32 v24, v15 offset:36868
	ds_write_b32 v25, v19 offset:36868
	v_add_u32_e32 v16, v6, v0
	v_cndmask_b32_e32 v2, v37, v36, vcc
	ds_read_b64 v[0:1], v16 offset:36864
	v_add_u32_e32 v17, v6, v2
	v_cndmask_b32_e32 v4, v35, v34, vcc
	ds_read_b64 v[2:3], v17 offset:36864
	v_add_u32_e32 v18, v6, v4
	v_cndmask_b32_e32 v7, v33, v32, vcc
	ds_read_b64 v[4:5], v18 offset:36864
	v_add_u32_e32 v20, v6, v7
	v_cndmask_b32_e32 v7, v31, v30, vcc
	ds_read_b64 v[8:9], v20 offset:36864
	v_add_u32_e32 v21, v6, v7
	v_cndmask_b32_e32 v7, v29, v28, vcc
	ds_read_b64 v[10:11], v21 offset:36864
	v_add_u32_e32 v22, v6, v7
	v_cndmask_b32_e32 v7, v233, v27, vcc
	ds_read_b64 v[12:13], v22 offset:36864
	v_add_u32_e32 v23, v6, v7
	v_cndmask_b32_e32 v7, 0, v26, vcc
	s_waitcnt lgkmcnt(5)
	v_fmac_f32_e32 v1, v19, v0
	ds_read_b64 v[14:15], v23 offset:36864
	v_add_u32_e32 v24, v6, v7
	s_waitcnt lgkmcnt(5)
	v_fmac_f32_e32 v3, v2, v1
	ds_read_b64 v[6:7], v24 offset:36864
	s_waitcnt lgkmcnt(5)
	v_fmac_f32_e32 v5, v4, v3
	s_waitcnt lgkmcnt(4)
	v_fmac_f32_e32 v9, v8, v5
	s_waitcnt lgkmcnt(3)
	v_fmac_f32_e32 v11, v10, v9
	s_waitcnt lgkmcnt(2)
	v_fmac_f32_e32 v13, v12, v11
	s_waitcnt lgkmcnt(1)
	v_fmac_f32_e32 v15, v14, v13
	s_waitcnt lgkmcnt(0)
	v_fmac_f32_e32 v7, v6, v15
	ds_write_b32 v16, v1 offset:36868
	ds_write_b32 v17, v3 offset:36868
	ds_write_b32 v18, v5 offset:36868
	ds_write_b32 v20, v9 offset:36868
	ds_write_b32 v21, v11 offset:36868
	ds_write_b32 v22, v13 offset:36868
	ds_write_b32 v23, v15 offset:36868
	ds_write_b32 v24, v7 offset:36868
